# mixer SGU + attention parts: cross-lane reductions (row max, row sum, sums of squares) through v_permlane16_swap / v_permlane32_swap instead of ds_bpermute + lgkmcnt waits; counted waits for the V fra
# speedup vs baseline: 1.0220x; 1.0010x over previous
; __device__ __forceinline__ void ss_add(ss_t* p, float sq) { const float fl = floorf(sq); const unsigned hi = (unsigned)fl, lo = (unsigned)((sq - fl) * 4294967296.0f); atomicAdd(p, ((ss_t)hi << 32) | (ss_t)lo); }
; __device__ __forceinline__ unsigned pkbf(float lo, float hi) { typedef float f2_t __attribute__((ext_vector_type(2))); typedef __bf16 b2_t __attribute__((ext_vector_type(2))); f2_t v = {lo, hi}; b2_t b = __builtin_convertvector(v, b2_t); return __builtin_bit_cast(unsigned, b); }
; __device__ __forceinline__ float bflo(unsigned w) { return __uint_as_float(w << 16); }
; __device__ __forceinline__ float bfhi(unsigned w) { return __uint_as_float(w & 0xffff0000u); }
; #define MFMA16(a, b, c) __builtin_amdgcn_mfma_f32_16x16x32_bf16((a), (b), (c), 0, 0, 0)
; __device__ __forceinline__ void mixer_phase256(const Args& A, int l, int vc, const bf16* Z, bf16* MIX, ss_t* ssa, ss_t* ssb, unsigned char* lds, int tid, int wid, int lane) {
;     ...
;         for (int j = 0; j < 4; ++j) {
;             const bf16* vn = VN + j * 64 * VN_STRIDE; const size_t tok = (size_t)((cb + j) * 128 + st); float sq = 0.f;
; #pragma unroll
;             for (int dt = 0; dt < 4; ++dt) {
;                 f32x4 acc = (f32x4){0.f, 0.f, 0.f, 0.f};
; #pragma unroll
;                 for (int ks = 0; ks < 4; ++ks) if (ks < nks) { const bf16x8 a = *(const bf16x8*)(vn + (16 * dt + fr) * VN_STRIDE + 32 * ks + 8 * fq); acc = MFMA16(a, bfr[ks], acc); }
;                 const float v0 = bflo(uw[j][dt].x) * (acc[0] + sbias), v1 = bfhi(uw[j][dt].x) * (acc[1] + sbias), v2 = bflo(uw[j][dt].y) * (acc[2] + sbias), v3 = bfhi(uw[j][dt].y) * (acc[3] + sbias);
;                 sq += (v0 * v0 + v1 * v1) + (v2 * v2 + v3 * v3);
;                 u32x2 w; w.x = pkbf(v0, v1); w.y = pkbf(v2, v3);
;                 *(u32x2*)(MIX + tok * DM + h * 64 + 16 * dt + 4 * fq) = w;
;             }
;             sq += __shfl_xor(sq, 16); sq += __shfl_xor(sq, 32); if (fq == 0) ss_add(ssa + tok, sq);
.Lsg2_m_2:
	s_nop 3
	v_lshlrev_b32_e32 v96, 16, v82
	v_and_b32_e32 v97, 0xffff0000, v82
	v_lshlrev_b32_e32 v98, 16, v83
	v_and_b32_e32 v99, 0xffff0000, v83
	v_pk_add_f32 v[194:195], v[112:113], v[194:195] op_sel_hi:[0,1]
	v_pk_add_f32 v[196:197], v[112:113], v[196:197] op_sel_hi:[0,1]
	v_pk_mul_f32 v[194:195], v[96:97], v[194:195]
	v_pk_mul_f32 v[196:197], v[98:99], v[196:197]
	v_pk_fma_f32 v[202:203], v[194:195], v[194:195], v[202:203]
	v_pk_fma_f32 v[202:203], v[196:197], v[196:197], v[202:203]
	v_cvt_pk_bf16_f32 v0, v194, v195
	v_cvt_pk_bf16_f32 v1, v196, v197
	global_store_dwordx2 v253, v[0:1], s[100:101] offset:64
	v_lshlrev_b32_e32 v96, 16, v80
	v_and_b32_e32 v97, 0xffff0000, v80
	v_lshlrev_b32_e32 v98, 16, v81
	v_and_b32_e32 v99, 0xffff0000, v81
	v_pk_add_f32 v[198:199], v[112:113], v[198:199] op_sel_hi:[0,1]
	v_pk_add_f32 v[200:201], v[112:113], v[200:201] op_sel_hi:[0,1]
	v_pk_mul_f32 v[198:199], v[96:97], v[198:199]
	v_pk_mul_f32 v[200:201], v[98:99], v[200:201]
	v_pk_fma_f32 v[202:203], v[198:199], v[198:199], v[202:203]
	v_pk_fma_f32 v[202:203], v[200:201], v[200:201], v[202:203]
	v_cvt_pk_bf16_f32 v46, v198, v199
	v_cvt_pk_bf16_f32 v47, v200, v201
	global_store_dwordx2 v253, v[46:47], s[100:101] offset:96
	v_add_f32_e32 v3, v202, v203
	v_mov_b32_e32 v45, v3
	s_nop 1
	v_permlane16_swap_b32_e32 v3, v45
	v_add_f32_e32 v3, v3, v45
	v_mov_b32_e32 v45, v3
	s_nop 1
	v_permlane32_swap_b32_e32 v3, v45
	v_add_f32_e32 v3, v3, v45
	s_mov_b64 exec, s[24:25]
	v_floor_f32_e32 v45, v3
	v_sub_f32_e32 v3, v3, v45
	v_mul_f32_e32 v3, 0x4f800000, v3
	v_cvt_u32_f32_e32 v79, v45
	v_cvt_u32_f32_e32 v78, v3
	global_atomic_add_x2 v254, v[78:79], s[100:101] offset:0
	s_mov_b64 exec, -1
	v_add_u32_e32 v253, 0x80000, v253
	s_waitcnt lgkmcnt(0)
	ds_read_b128 v[12:15], v100 offset:34816
	ds_read_b128 v[28:31], v100 offset:39168
	s_cmp_lt_u32 s23, 1
	s_cbranch_scc1 .Lsg2_r_4
	ds_read_b128 v[16:19], v100 offset:34880
	ds_read_b128 v[32:35], v100 offset:39232
	s_cmp_lt_u32 s23, 2
	s_cbranch_scc1 .Lsg2_r_4
	ds_read_b128 v[20:23], v100 offset:34944
	ds_read_b128 v[36:39], v100 offset:39296
	s_cmp_lt_u32 s23, 3
	s_cbranch_scc1 .Lsg2_r_4
	ds_read_b128 v[24:27], v100 offset:35008
	ds_read_b128 v[40:43], v100 offset:39360

; __device__ __forceinline__ void ss_add(ss_t* p, float sq) { const float fl = floorf(sq); const unsigned hi = (unsigned)fl, lo = (unsigned)((sq - fl) * 4294967296.0f); atomicAdd(p, ((ss_t)hi << 32) | (ss_t)lo); }
; __device__ __forceinline__ unsigned pkbf(float lo, float hi) { typedef float f2_t __attribute__((ext_vector_type(2))); typedef __bf16 b2_t __attribute__((ext_vector_type(2))); f2_t v = {lo, hi}; b2_t b = __builtin_convertvector(v, b2_t); return __builtin_bit_cast(unsigned, b); }
; __device__ __forceinline__ float bflo(unsigned w) { return __uint_as_float(w << 16); }
; __device__ __forceinline__ float bfhi(unsigned w) { return __uint_as_float(w & 0xffff0000u); }
; #define MFMA16(a, b, c) __builtin_amdgcn_mfma_f32_16x16x32_bf16((a), (b), (c), 0, 0, 0)
; __device__ __forceinline__ void mixer_phase256(const Args& A, int l, int vc, const bf16* Z, bf16* MIX, ss_t* ssa, ss_t* ssb, unsigned char* lds, int tid, int wid, int lane) {
;     ...
;         for (int j = 0; j < 4; ++j) {
;             const bf16* vn = VN + j * 64 * VN_STRIDE; const size_t tok = (size_t)((cb + j) * 128 + st); float sq = 0.f;
; #pragma unroll
;             for (int dt = 0; dt < 4; ++dt) {
;                 f32x4 acc = (f32x4){0.f, 0.f, 0.f, 0.f};
; #pragma unroll
;                 for (int ks = 0; ks < 4; ++ks) if (ks < nks) { const bf16x8 a = *(const bf16x8*)(vn + (16 * dt + fr) * VN_STRIDE + 32 * ks + 8 * fq); acc = MFMA16(a, bfr[ks], acc); }
;                 const float v0 = bflo(uw[j][dt].x) * (acc[0] + sbias), v1 = bfhi(uw[j][dt].x) * (acc[1] + sbias), v2 = bflo(uw[j][dt].y) * (acc[2] + sbias), v3 = bfhi(uw[j][dt].y) * (acc[3] + sbias);
;                 sq += (v0 * v0 + v1 * v1) + (v2 * v2 + v3 * v3);
;                 u32x2 w; w.x = pkbf(v0, v1); w.y = pkbf(v2, v3);
;                 *(u32x2*)(MIX + tok * DM + h * 64 + 16 * dt + 4 * fq) = w;
;             }
;             sq += __shfl_xor(sq, 16); sq += __shfl_xor(sq, 32); if (fq == 0) ss_add(ssa + tok, sq);
.Lsg2_m_4:
	s_nop 3
	v_lshlrev_b32_e32 v96, 16, v70
	v_and_b32_e32 v97, 0xffff0000, v70
	v_lshlrev_b32_e32 v98, 16, v71
	v_and_b32_e32 v99, 0xffff0000, v71
	v_pk_add_f32 v[194:195], v[112:113], v[194:195] op_sel_hi:[0,1]
	v_pk_add_f32 v[196:197], v[112:113], v[196:197] op_sel_hi:[0,1]
	v_pk_mul_f32 v[194:195], v[96:97], v[194:195]
	v_pk_mul_f32 v[196:197], v[98:99], v[196:197]
	v_pk_fma_f32 v[202:203], v[194:195], v[194:195], v[202:203]
	v_pk_fma_f32 v[202:203], v[196:197], v[196:197], v[202:203]
	v_cvt_pk_bf16_f32 v0, v194, v195
	v_cvt_pk_bf16_f32 v1, v196, v197
	global_store_dwordx2 v253, v[0:1], s[100:101] offset:64
	v_lshlrev_b32_e32 v96, 16, v68
	v_and_b32_e32 v97, 0xffff0000, v68
	v_lshlrev_b32_e32 v98, 16, v69
	v_and_b32_e32 v99, 0xffff0000, v69
	v_pk_add_f32 v[198:199], v[112:113], v[198:199] op_sel_hi:[0,1]
	v_pk_add_f32 v[200:201], v[112:113], v[200:201] op_sel_hi:[0,1]
	v_pk_mul_f32 v[198:199], v[96:97], v[198:199]
	v_pk_mul_f32 v[200:201], v[98:99], v[200:201]
	v_pk_fma_f32 v[202:203], v[198:199], v[198:199], v[202:203]
	v_pk_fma_f32 v[202:203], v[200:201], v[200:201], v[202:203]
	v_cvt_pk_bf16_f32 v46, v198, v199
	v_cvt_pk_bf16_f32 v47, v200, v201
	global_store_dwordx2 v253, v[46:47], s[100:101] offset:96
	v_add_f32_e32 v3, v202, v203
	v_mov_b32_e32 v45, v3
	s_nop 1
	v_permlane16_swap_b32_e32 v3, v45
	v_add_f32_e32 v3, v3, v45
	v_mov_b32_e32 v45, v3
	s_nop 1
	v_permlane32_swap_b32_e32 v3, v45
	v_add_f32_e32 v3, v3, v45
	s_mov_b64 exec, s[24:25]
	v_floor_f32_e32 v45, v3
	v_sub_f32_e32 v3, v3, v45
	v_mul_f32_e32 v3, 0x4f800000, v3
	v_cvt_u32_f32_e32 v79, v45
	v_cvt_u32_f32_e32 v78, v3
	global_atomic_add_x2 v254, v[78:79], s[100:101] offset:1024
	s_mov_b64 exec, -1
	v_add_u32_e32 v253, 0x80000, v253
	s_waitcnt lgkmcnt(0)
	ds_read_b128 v[12:15], v100 offset:52224
	ds_read_b128 v[28:31], v100 offset:56576
	s_cmp_lt_u32 s23, 1
	s_cbranch_scc1 .Lsg2_r_6
	ds_read_b128 v[16:19], v100 offset:52288
	ds_read_b128 v[32:35], v100 offset:56640
	s_cmp_lt_u32 s23, 2
	s_cbranch_scc1 .Lsg2_r_6
	ds_read_b128 v[20:23], v100 offset:52352
	ds_read_b128 v[36:39], v100 offset:56704
	s_cmp_lt_u32 s23, 3
	s_cbranch_scc1 .Lsg2_r_6
	ds_read_b128 v[24:27], v100 offset:52416
	ds_read_b128 v[40:43], v100 offset:56768

; __device__ __forceinline__ void ss_add(ss_t* p, float sq) { const float fl = floorf(sq); const unsigned hi = (unsigned)fl, lo = (unsigned)((sq - fl) * 4294967296.0f); atomicAdd(p, ((ss_t)hi << 32) | (ss_t)lo); }
; __device__ __forceinline__ unsigned pkbf(float lo, float hi) { typedef float f2_t __attribute__((ext_vector_type(2))); typedef __bf16 b2_t __attribute__((ext_vector_type(2))); f2_t v = {lo, hi}; b2_t b = __builtin_convertvector(v, b2_t); return __builtin_bit_cast(unsigned, b); }
; __device__ __forceinline__ float bflo(unsigned w) { return __uint_as_float(w << 16); }
; __device__ __forceinline__ float bfhi(unsigned w) { return __uint_as_float(w & 0xffff0000u); }
; #define MFMA16(a, b, c) __builtin_amdgcn_mfma_f32_16x16x32_bf16((a), (b), (c), 0, 0, 0)
; __device__ __forceinline__ void mixer_phase256(const Args& A, int l, int vc, const bf16* Z, bf16* MIX, ss_t* ssa, ss_t* ssb, unsigned char* lds, int tid, int wid, int lane) {
;     ...
;         for (int j = 0; j < 4; ++j) {
;             const bf16* vn = VN + j * 64 * VN_STRIDE; const size_t tok = (size_t)((cb + j) * 128 + st); float sq = 0.f;
; #pragma unroll
;             for (int dt = 0; dt < 4; ++dt) {
;                 f32x4 acc = (f32x4){0.f, 0.f, 0.f, 0.f};
; #pragma unroll
;                 for (int ks = 0; ks < 4; ++ks) if (ks < nks) { const bf16x8 a = *(const bf16x8*)(vn + (16 * dt + fr) * VN_STRIDE + 32 * ks + 8 * fq); acc = MFMA16(a, bfr[ks], acc); }
;                 const float v0 = bflo(uw[j][dt].x) * (acc[0] + sbias), v1 = bfhi(uw[j][dt].x) * (acc[1] + sbias), v2 = bflo(uw[j][dt].y) * (acc[2] + sbias), v3 = bfhi(uw[j][dt].y) * (acc[3] + sbias);
;                 sq += (v0 * v0 + v1 * v1) + (v2 * v2 + v3 * v3);
;                 u32x2 w; w.x = pkbf(v0, v1); w.y = pkbf(v2, v3);
;                 *(u32x2*)(MIX + tok * DM + h * 64 + 16 * dt + 4 * fq) = w;
;             }
;             sq += __shfl_xor(sq, 16); sq += __shfl_xor(sq, 32); if (fq == 0) ss_add(ssa + tok, sq);
;         }
.Lsg2_m_6:
	s_nop 3
	v_lshlrev_b32_e32 v96, 16, v60
	v_and_b32_e32 v97, 0xffff0000, v60
	v_lshlrev_b32_e32 v98, 16, v61
	v_and_b32_e32 v99, 0xffff0000, v61
	v_pk_add_f32 v[194:195], v[112:113], v[194:195] op_sel_hi:[0,1]
	v_pk_add_f32 v[196:197], v[112:113], v[196:197] op_sel_hi:[0,1]
	v_pk_mul_f32 v[194:195], v[96:97], v[194:195]
	v_pk_mul_f32 v[196:197], v[98:99], v[196:197]
	v_pk_fma_f32 v[202:203], v[194:195], v[194:195], v[202:203]
	v_pk_fma_f32 v[202:203], v[196:197], v[196:197], v[202:203]
	v_cvt_pk_bf16_f32 v0, v194, v195
	v_cvt_pk_bf16_f32 v1, v196, v197
	global_store_dwordx2 v253, v[0:1], s[100:101] offset:64
	v_lshlrev_b32_e32 v96, 16, v58
	v_and_b32_e32 v97, 0xffff0000, v58
	v_lshlrev_b32_e32 v98, 16, v59
	v_and_b32_e32 v99, 0xffff0000, v59
	v_pk_add_f32 v[198:199], v[112:113], v[198:199] op_sel_hi:[0,1]
	v_pk_add_f32 v[200:201], v[112:113], v[200:201] op_sel_hi:[0,1]
	v_pk_mul_f32 v[198:199], v[96:97], v[198:199]
	v_pk_mul_f32 v[200:201], v[98:99], v[200:201]
	v_pk_fma_f32 v[202:203], v[198:199], v[198:199], v[202:203]
	v_pk_fma_f32 v[202:203], v[200:201], v[200:201], v[202:203]
	v_cvt_pk_bf16_f32 v46, v198, v199
	v_cvt_pk_bf16_f32 v47, v200, v201
	global_store_dwordx2 v253, v[46:47], s[100:101] offset:96
	v_add_f32_e32 v3, v202, v203
	v_mov_b32_e32 v45, v3
	s_nop 1
	v_permlane16_swap_b32_e32 v3, v45
	v_add_f32_e32 v3, v3, v45
	v_mov_b32_e32 v45, v3
	s_nop 1
	v_permlane32_swap_b32_e32 v3, v45
	v_add_f32_e32 v3, v3, v45
	s_mov_b64 exec, s[24:25]
	v_floor_f32_e32 v45, v3
	v_sub_f32_e32 v3, v3, v45
	v_mul_f32_e32 v3, 0x4f800000, v3
	v_cvt_u32_f32_e32 v79, v45
	v_cvt_u32_f32_e32 v78, v3
	global_atomic_add_x2 v254, v[78:79], s[100:101] offset:2048
	s_mov_b64 exec, -1
	v_add_u32_e32 v253, 0x80000, v253
	s_waitcnt lgkmcnt(0)
	v_mfma_f32_16x16x32_bf16 v[194:197], v[212:215], v[4:7], 0
	v_mfma_f32_16x16x32_bf16 v[198:201], v[228:231], v[4:7], 0
	s_cmp_lt_u32 s23, 1
	s_cbranch_scc1 .Lsg2_m_7
	v_mfma_f32_16x16x32_bf16 v[194:197], v[216:219], v[8:11], v[194:197]
	v_mfma_f32_16x16x32_bf16 v[198:201], v[232:235], v[8:11], v[198:201]
	s_cmp_lt_u32 s23, 2
	s_cbranch_scc1 .Lsg2_m_7
	v_mfma_f32_16x16x32_bf16 v[194:197], v[220:223], v[88:91], v[194:197]
	v_mfma_f32_16x16x32_bf16 v[198:201], v[236:239], v[88:91], v[198:201]
	s_cmp_lt_u32 s23, 3
	s_cbranch_scc1 .Lsg2_m_7
	v_mfma_f32_16x16x32_bf16 v[194:197], v[224:227], v[92:95], v[194:197]
	v_mfma_f32_16x16x32_bf16 v[198:201], v[240:243], v[92:95], v[198:201]
.Lsg2_m_7:
	s_waitcnt vmcnt(28)
	s_nop 3
	v_lshlrev_b32_e32 v96, 16, v54
	v_and_b32_e32 v97, 0xffff0000, v54
	v_lshlrev_b32_e32 v98, 16, v55
	v_and_b32_e32 v99, 0xffff0000, v55
	v_pk_add_f32 v[186:187], v[112:113], v[186:187] op_sel_hi:[0,1]
	v_pk_add_f32 v[188:189], v[112:113], v[188:189] op_sel_hi:[0,1]
	v_pk_mul_f32 v[186:187], v[96:97], v[186:187]
	v_pk_mul_f32 v[188:189], v[98:99], v[188:189]
	v_pk_mul_f32 v[202:203], v[186:187], v[186:187]
	v_pk_fma_f32 v[202:203], v[188:189], v[188:189], v[202:203]
	v_cvt_pk_bf16_f32 v0, v186, v187
	v_cvt_pk_bf16_f32 v1, v188, v189
	global_store_dwordx2 v253, v[0:1], s[100:101] offset:0
	v_lshlrev_b32_e32 v96, 16, v52
	v_and_b32_e32 v97, 0xffff0000, v52
	v_lshlrev_b32_e32 v98, 16, v53
	v_and_b32_e32 v99, 0xffff0000, v53
	v_pk_add_f32 v[190:191], v[112:113], v[190:191] op_sel_hi:[0,1]
	v_pk_add_f32 v[192:193], v[112:113], v[192:193] op_sel_hi:[0,1]
	v_pk_mul_f32 v[190:191], v[96:97], v[190:191]
	v_pk_mul_f32 v[192:193], v[98:99], v[192:193]
	v_pk_fma_f32 v[202:203], v[190:191], v[190:191], v[202:203]
	v_pk_fma_f32 v[202:203], v[192:193], v[192:193], v[202:203]
	v_cvt_pk_bf16_f32 v46, v190, v191
	v_cvt_pk_bf16_f32 v47, v192, v193
	global_store_dwordx2 v253, v[46:47], s[100:101] offset:32
	s_nop 7
	s_nop 0
	v_lshlrev_b32_e32 v96, 16, v50
	v_and_b32_e32 v97, 0xffff0000, v50
	v_lshlrev_b32_e32 v98, 16, v51
	v_and_b32_e32 v99, 0xffff0000, v51
	v_pk_add_f32 v[194:195], v[112:113], v[194:195] op_sel_hi:[0,1]
	v_pk_add_f32 v[196:197], v[112:113], v[196:197] op_sel_hi:[0,1]
	v_pk_mul_f32 v[194:195], v[96:97], v[194:195]
	v_pk_mul_f32 v[196:197], v[98:99], v[196:197]
	v_pk_fma_f32 v[202:203], v[194:195], v[194:195], v[202:203]
	v_pk_fma_f32 v[202:203], v[196:197], v[196:197], v[202:203]
	v_cvt_pk_bf16_f32 v0, v194, v195
	v_cvt_pk_bf16_f32 v1, v196, v197
	global_store_dwordx2 v253, v[0:1], s[100:101] offset:64
	v_lshlrev_b32_e32 v96, 16, v48
	v_and_b32_e32 v97, 0xffff0000, v48
	v_lshlrev_b32_e32 v98, 16, v49
	v_and_b32_e32 v99, 0xffff0000, v49
	v_pk_add_f32 v[198:199], v[112:113], v[198:199] op_sel_hi:[0,1]
	v_pk_add_f32 v[200:201], v[112:113], v[200:201] op_sel_hi:[0,1]
	v_pk_mul_f32 v[198:199], v[96:97], v[198:199]
	v_pk_mul_f32 v[200:201], v[98:99], v[200:201]
	v_pk_fma_f32 v[202:203], v[198:199], v[198:199], v[202:203]
	v_pk_fma_f32 v[202:203], v[200:201], v[200:201], v[202:203]
	v_cvt_pk_bf16_f32 v46, v198, v199
	v_cvt_pk_bf16_f32 v47, v200, v201
	global_store_dwordx2 v253, v[46:47], s[100:101] offset:96
	v_add_f32_e32 v3, v202, v203
	v_mov_b32_e32 v45, v3
	s_nop 1
	v_permlane16_swap_b32_e32 v3, v45
	v_add_f32_e32 v3, v3, v45
	v_mov_b32_e32 v45, v3
	s_nop 1
	v_permlane32_swap_b32_e32 v3, v45
	v_add_f32_e32 v3, v3, v45
	s_mov_b64 exec, s[24:25]
	v_floor_f32_e32 v45, v3
	v_sub_f32_e32 v3, v3, v45
	v_mul_f32_e32 v3, 0x4f800000, v3
	v_cvt_u32_f32_e32 v79, v45
	v_cvt_u32_f32_e32 v78, v3
	global_atomic_add_x2 v254, v[78:79], s[100:101] offset:3072
	s_mov_b64 exec, -1
	s_branch .Lsg2_done

; __device__ __forceinline__ float bflo(unsigned w) { return __uint_as_float(w << 16); }
; __device__ __forceinline__ float bfhi(unsigned w) { return __uint_as_float(w & 0xffff0000u); }
; template <int PAR> __device__ __forceinline__ void attn_sub(const bf16* KS, const bf16* VT, const float* BTg, const float* gq, float sink2, int n, int ti, int hq, const u32x4 w0, const u32x4 w1, bf16* MIX, ss_t* ssb, int lane) {
;     ...
;     { float f0[8], f1[8]; float ss = 0.f;
; #pragma unroll
;       for (int e = 0; e < 4; ++e) { f0[2 * e] = bflo(w0[e]); f0[2 * e + 1] = bfhi(w0[e]); f1[2 * e] = bflo(w1[e]); f1[2 * e + 1] = bfhi(w1[e]);
;           ss += (f0[2 * e] * f0[2 * e] + f0[2 * e + 1] * f0[2 * e + 1]) + (f1[2 * e] * f1[2 * e] + f1[2 * e + 1] * f1[2 * e + 1]); }
; __device__ __forceinline__ void attn_compute(const Args& A, int l, int n, int kvh, const u32x4 (&q0)[2], const bf16* Z, bf16* MIX, ss_t* ssb, unsigned char* lds, int wid, int lane) {
;     const bf16* KS = (const bf16*)(lds + LDS_KS); const bf16* VT = (const bf16*)(lds + LDS_VT); const float* BT = (const float*)(lds + LDS_BT);
;     const float* gq = A.q_norm_g + l * 64;
;     const int g = wid >> 1, qh = wid & 1, hq = kvh * 4 + g; const int fr = lane & 15, fq = lane >> 4;
;     const float sink2 = A.sinks[l * 16 + hq] * 1.4426950408889634f;
;     const float* BTg = BT + g * 128;
;     u32x4 qc0 = q0[0], qc1 = q0[1];
.Lsg2_done:
	s_waitcnt vmcnt(20)
	v_readlane_b32 s100, v250, 28
	v_readlane_b32 s101, v250, 29
	v_readlane_b32 s24, v249, 63
	v_readlane_b32 s23, v248, 1
	s_lshr_b32 s20, s73, 1
	s_and_b32 s21, s73, 1
	s_lshl_b32 s26, s21, 2
	v_and_b32_e32 v200, 15, v174
	v_lshrrev_b32_e32 v201, 4, v174
	s_add_i32 s22, s24, s20
	s_cmp_gt_i32 s23, 0
	s_cselect_b64 s[36:37], -1, 0
	v_lshlrev_b32_e32 v202, 2, v201
	v_add_u32_e32 v203, 0, v202
	v_cmp_gt_i32_e64 s[40:41], v203, v200
	v_add_u32_e32 v203, 1, v202
	v_cmp_gt_i32_e64 s[42:43], v203, v200
	v_add_u32_e32 v203, 2, v202
	v_cmp_gt_i32_e64 s[44:45], v203, v200
	v_add_u32_e32 v203, 3, v202
	v_cmp_gt_i32_e64 s[46:47], v203, v200
	v_cmp_eq_u32_e64 s[56:57], 0, v201
	v_mov_b32_e32 v203, s21
	v_lshl_add_u32 v185, v203, 6, v200
	v_mul_u32_u24_e32 v185, 0x90, v185
	v_lshl_add_u32 v185, v201, 4, v185
	v_lshlrev_b32_e32 v186, 2, v200
	v_lshlrev_b32_e32 v0, 4, v201
	v_sub_u32_e32 v186, v186, v0
	s_lshl_b32 s27, s20, 9
	s_add_i32 s27, s27, 0x113f4
	v_add_u32_e32 v186, s27, v186
	v_mul_u32_u24_e32 v187, 0x210, v200
	v_lshl_add_u32 v187, v203, 7, v187
	v_lshl_add_u32 v187, v201, 3, v187
	v_add_u32_e32 v187, 0x9000, v187
	v_add_u32_e32 v188, 0x2100, v187
	v_add_u32_e32 v189, 0x4200, v187
	v_add_u32_e32 v190, 0x6300, v187
	v_lshl_add_u32 v0, v203, 6, v200
	v_add_u32_e32 v0, s23, v0
	v_lshlrev_b32_e32 v191, 12, v0
	s_lshl_b32 s27, s22, 7
	s_add_i32 s27, s27, 0x1ba00800
	v_add_u32_e32 v191, s27, v191
	v_lshl_add_u32 v191, v201, 3, v191
	s_add_i32 s27, s78, 13
	s_lshl_b32 s27, s27, 16
	v_lshl_add_u32 v192, v0, 3, s27
	v_xor_b32_e32 v193, 16, v174
	v_lshlrev_b32_e32 v193, 2, v193
	v_xor_b32_e32 v194, 32, v174
	v_lshlrev_b32_e32 v194, 2, v194
	v_mov_b32_e32 v195, 0xf149f2ca
	v_mul_f32_e32 v184, 0x3fb8aa3b, v184
	v_lshlrev_b32_e32 v4, 16, v116
	v_and_b32_e32 v5, 0xffff0000, v116
	v_lshlrev_b32_e32 v6, 16, v117
	v_and_b32_e32 v7, 0xffff0000, v117
	v_lshlrev_b32_e32 v8, 16, v118
	v_and_b32_e32 v9, 0xffff0000, v118
	v_lshlrev_b32_e32 v10, 16, v119
	v_and_b32_e32 v11, 0xffff0000, v119
	v_lshlrev_b32_e32 v12, 16, v120
	v_and_b32_e32 v13, 0xffff0000, v120
	v_lshlrev_b32_e32 v14, 16, v121
	v_and_b32_e32 v15, 0xffff0000, v121
	v_lshlrev_b32_e32 v16, 16, v122
	v_and_b32_e32 v17, 0xffff0000, v122
	v_lshlrev_b32_e32 v18, 16, v123
	v_and_b32_e32 v19, 0xffff0000, v123
	v_pk_mul_f32 v[78:79], v[4:5], v[4:5]
	v_pk_fma_f32 v[78:79], v[6:7], v[6:7], v[78:79]
	v_pk_fma_f32 v[78:79], v[8:9], v[8:9], v[78:79]
	v_pk_fma_f32 v[78:79], v[10:11], v[10:11], v[78:79]
	v_pk_fma_f32 v[78:79], v[12:13], v[12:13], v[78:79]
	v_pk_fma_f32 v[78:79], v[14:15], v[14:15], v[78:79]
	v_pk_fma_f32 v[78:79], v[16:17], v[16:17], v[78:79]
	v_pk_fma_f32 v[78:79], v[18:19], v[18:19], v[78:79]
	v_add_f32_e32 v45, v78, v79
	v_lshlrev_b32_e32 v20, 16, v124
	v_and_b32_e32 v21, 0xffff0000, v124
	v_lshlrev_b32_e32 v22, 16, v125
	v_and_b32_e32 v23, 0xffff0000, v125
	v_lshlrev_b32_e32 v24, 16, v126
	v_and_b32_e32 v25, 0xffff0000, v126
	v_lshlrev_b32_e32 v26, 16, v127
	v_and_b32_e32 v27, 0xffff0000, v127
	v_lshlrev_b32_e32 v28, 16, v128
	v_and_b32_e32 v29, 0xffff0000, v128
	v_lshlrev_b32_e32 v30, 16, v129
	v_and_b32_e32 v31, 0xffff0000, v129
	v_lshlrev_b32_e32 v32, 16, v130
	v_and_b32_e32 v33, 0xffff0000, v130
	v_lshlrev_b32_e32 v34, 16, v131
	v_and_b32_e32 v35, 0xffff0000, v131
	v_pk_mul_f32 v[80:81], v[20:21], v[20:21]
	v_pk_fma_f32 v[80:81], v[22:23], v[22:23], v[80:81]
	v_pk_fma_f32 v[80:81], v[24:25], v[24:25], v[80:81]
	v_pk_fma_f32 v[80:81], v[26:27], v[26:27], v[80:81]
	v_pk_fma_f32 v[80:81], v[28:29], v[28:29], v[80:81]
	v_pk_fma_f32 v[80:81], v[30:31], v[30:31], v[80:81]
	v_pk_fma_f32 v[80:81], v[32:33], v[32:33], v[80:81]
	v_pk_fma_f32 v[80:81], v[34:35], v[34:35], v[80:81]
	v_add_f32_e32 v46, v80, v81
	v_lshlrev_b32_e32 v212, 16, v132
	v_and_b32_e32 v213, 0xffff0000, v132
	v_lshlrev_b32_e32 v214, 16, v133
	v_and_b32_e32 v215, 0xffff0000, v133
	v_lshlrev_b32_e32 v216, 16, v134
	v_and_b32_e32 v217, 0xffff0000, v134
	v_lshlrev_b32_e32 v218, 16, v135
	v_and_b32_e32 v219, 0xffff0000, v135
	v_lshlrev_b32_e32 v220, 16, v136
	v_and_b32_e32 v221, 0xffff0000, v136
	v_lshlrev_b32_e32 v222, 16, v137
	v_and_b32_e32 v223, 0xffff0000, v137
	v_lshlrev_b32_e32 v224, 16, v138
	v_and_b32_e32 v225, 0xffff0000, v138
	v_lshlrev_b32_e32 v226, 16, v139
	v_and_b32_e32 v227, 0xffff0000, v139
	v_pk_mul_f32 v[96:97], v[212:213], v[212:213]
	v_pk_fma_f32 v[96:97], v[214:215], v[214:215], v[96:97]
	v_pk_fma_f32 v[96:97], v[216:217], v[216:217], v[96:97]
	v_pk_fma_f32 v[96:97], v[218:219], v[218:219], v[96:97]
	v_pk_fma_f32 v[96:97], v[220:221], v[220:221], v[96:97]
	v_pk_fma_f32 v[96:97], v[222:223], v[222:223], v[96:97]
	v_pk_fma_f32 v[96:97], v[224:225], v[224:225], v[96:97]
	v_pk_fma_f32 v[96:97], v[226:227], v[226:227], v[96:97]
	v_add_f32_e32 v47, v96, v97
	v_lshlrev_b32_e32 v228, 16, v140
	v_and_b32_e32 v229, 0xffff0000, v140
	v_lshlrev_b32_e32 v230, 16, v141
	v_and_b32_e32 v231, 0xffff0000, v141
	v_lshlrev_b32_e32 v232, 16, v142
	v_and_b32_e32 v233, 0xffff0000, v142
	v_lshlrev_b32_e32 v234, 16, v143
	v_and_b32_e32 v235, 0xffff0000, v143
	v_lshlrev_b32_e32 v236, 16, v144
	v_and_b32_e32 v237, 0xffff0000, v144
	v_lshlrev_b32_e32 v238, 16, v145
	v_and_b32_e32 v239, 0xffff0000, v145
	v_lshlrev_b32_e32 v240, 16, v146
	v_and_b32_e32 v241, 0xffff0000, v146
	v_lshlrev_b32_e32 v242, 16, v147
	v_and_b32_e32 v243, 0xffff0000, v147
	v_pk_mul_f32 v[98:99], v[228:229], v[228:229]
	v_pk_fma_f32 v[98:99], v[230:231], v[230:231], v[98:99]
	v_pk_fma_f32 v[98:99], v[232:233], v[232:233], v[98:99]
	v_pk_fma_f32 v[98:99], v[234:235], v[234:235], v[98:99]
	v_pk_fma_f32 v[98:99], v[236:237], v[236:237], v[98:99]
; __device__ __forceinline__ unsigned pkbf(float lo, float hi) { typedef float f2_t __attribute__((ext_vector_type(2))); typedef __bf16 b2_t __attribute__((ext_vector_type(2))); f2_t v = {lo, hi}; b2_t b = __builtin_convertvector(v, b2_t); return __builtin_bit_cast(unsigned, b); }
; template <int PAR> __device__ __forceinline__ void attn_sub(const bf16* KS, const bf16* VT, const float* BTg, const float* gq, float sink2, int n, int ti, int hq, const u32x4 w0, const u32x4 w1, bf16* MIX, ss_t* ssb, int lane) {
;     ...
;       ss += __shfl_xor(ss, 16); ss += __shfl_xor(ss, 32);
;       const float rs = (0.125f * 1.4426950408889634f) / sqrtf(ss * (1.0f / 64.f) + EPS);
;       const f32x4 a0 = *(const f32x4*)(gq + 8 * fq), a1 = *(const f32x4*)(gq + 8 * fq + 4), b0 = *(const f32x4*)(gq + 32 + 8 * fq), b1 = *(const f32x4*)(gq + 32 + 8 * fq + 4);
;       u32x4 p0, p1;
;       p0.x = pkbf(f0[0] * rs * a0.x, f0[1] * rs * a0.y); p0.y = pkbf(f0[2] * rs * a0.z, f0[3] * rs * a0.w); p0.z = pkbf(f0[4] * rs * a1.x, f0[5] * rs * a1.y); p0.w = pkbf(f0[6] * rs * a1.z, f0[7] * rs * a1.w);
;       p1.x = pkbf(f1[0] * rs * b0.x, f1[1] * rs * b0.y); p1.y = pkbf(f1[2] * rs * b0.z, f1[3] * rs * b0.w); p1.z = pkbf(f1[4] * rs * b1.x, f1[5] * rs * b1.y); p1.w = pkbf(f1[6] * rs * b1.z, f1[7] * rs * b1.w);
;       qf[0] = __builtin_bit_cast(bf16x8, p0); qf[1] = __builtin_bit_cast(bf16x8, p1); }
;     const int e0 = 4 * fq - fr;
;     const float* bp = BTg + (128 - 16 * 8 - 3 - e0);
	v_pk_fma_f32 v[98:99], v[238:239], v[238:239], v[98:99]
	v_pk_fma_f32 v[98:99], v[240:241], v[240:241], v[98:99]
	v_pk_fma_f32 v[98:99], v[242:243], v[242:243], v[98:99]
	v_add_f32_e32 v76, v98, v99
	v_mov_b32_e32 v0, v45
	v_mov_b32_e32 v1, v46
	v_mov_b32_e32 v3, v47
	v_mov_b32_e32 v100, v76
	v_permlane16_swap_b32_e32 v45, v0
	v_permlane16_swap_b32_e32 v46, v1
	v_permlane16_swap_b32_e32 v47, v3
	v_permlane16_swap_b32_e32 v76, v100
	v_add_f32_e32 v45, v45, v0
	v_add_f32_e32 v46, v46, v1
	v_add_f32_e32 v47, v47, v3
	v_add_f32_e32 v76, v76, v100
	v_mov_b32_e32 v0, v45
	v_mov_b32_e32 v1, v46
	v_mov_b32_e32 v3, v47
	v_mov_b32_e32 v100, v76
	v_permlane32_swap_b32_e32 v45, v0
	v_permlane32_swap_b32_e32 v46, v1
	v_permlane32_swap_b32_e32 v47, v3
	v_permlane32_swap_b32_e32 v76, v100
	v_add_f32_e32 v45, v45, v0
	v_add_f32_e32 v46, v46, v1
	v_add_f32_e32 v47, v47, v3
	v_add_f32_e32 v76, v76, v100
	v_fmamk_f32 v45, v45, 0x3c800000, v205
	v_fmamk_f32 v46, v46, 0x3c800000, v205
	v_fmamk_f32 v47, v47, 0x3c800000, v205
	v_fmamk_f32 v76, v76, 0x3c800000, v205
	v_rsq_f32_e32 v45, v45
	v_rsq_f32_e32 v46, v46
	v_rsq_f32_e32 v47, v47
	v_rsq_f32_e32 v76, v76
	s_nop 0
	v_mul_f32_e32 v78, 0x3e38aa3b, v45
	v_mul_f32_e32 v80, 0x3e38aa3b, v46
	v_mul_f32_e32 v96, 0x3e38aa3b, v47
	v_mul_f32_e32 v98, 0x3e38aa3b, v76
	v_pk_mul_f32 v[4:5], v[78:79], v[4:5] op_sel_hi:[0,1]
	v_pk_mul_f32 v[4:5], v[4:5], v[148:149]
	v_cvt_pk_bf16_f32 v116, v4, v5
	v_pk_mul_f32 v[6:7], v[78:79], v[6:7] op_sel_hi:[0,1]
	v_pk_mul_f32 v[6:7], v[6:7], v[150:151]
	v_cvt_pk_bf16_f32 v117, v6, v7
	v_pk_mul_f32 v[8:9], v[78:79], v[8:9] op_sel_hi:[0,1]
	v_pk_mul_f32 v[8:9], v[8:9], v[152:153]
	v_cvt_pk_bf16_f32 v118, v8, v9
	v_pk_mul_f32 v[10:11], v[78:79], v[10:11] op_sel_hi:[0,1]
	v_pk_mul_f32 v[10:11], v[10:11], v[154:155]
	v_cvt_pk_bf16_f32 v119, v10, v11
	v_pk_mul_f32 v[12:13], v[78:79], v[12:13] op_sel_hi:[0,1]
	v_pk_mul_f32 v[12:13], v[12:13], v[156:157]
	v_cvt_pk_bf16_f32 v120, v12, v13
	v_pk_mul_f32 v[14:15], v[78:79], v[14:15] op_sel_hi:[0,1]
	v_pk_mul_f32 v[14:15], v[14:15], v[158:159]
	v_cvt_pk_bf16_f32 v121, v14, v15
	v_pk_mul_f32 v[16:17], v[78:79], v[16:17] op_sel_hi:[0,1]
	v_pk_mul_f32 v[16:17], v[16:17], v[180:181]
	v_cvt_pk_bf16_f32 v122, v16, v17
	v_pk_mul_f32 v[18:19], v[78:79], v[18:19] op_sel_hi:[0,1]
	v_pk_mul_f32 v[18:19], v[18:19], v[182:183]
	v_cvt_pk_bf16_f32 v123, v18, v19
	v_pk_mul_f32 v[20:21], v[80:81], v[20:21] op_sel_hi:[0,1]
	v_pk_mul_f32 v[20:21], v[20:21], v[148:149]
	v_cvt_pk_bf16_f32 v124, v20, v21
	v_pk_mul_f32 v[22:23], v[80:81], v[22:23] op_sel_hi:[0,1]
	v_pk_mul_f32 v[22:23], v[22:23], v[150:151]
	v_cvt_pk_bf16_f32 v125, v22, v23
	v_pk_mul_f32 v[24:25], v[80:81], v[24:25] op_sel_hi:[0,1]
	v_pk_mul_f32 v[24:25], v[24:25], v[152:153]
	v_cvt_pk_bf16_f32 v126, v24, v25
	v_pk_mul_f32 v[26:27], v[80:81], v[26:27] op_sel_hi:[0,1]
	v_pk_mul_f32 v[26:27], v[26:27], v[154:155]
	v_cvt_pk_bf16_f32 v127, v26, v27
	v_pk_mul_f32 v[28:29], v[80:81], v[28:29] op_sel_hi:[0,1]
	v_pk_mul_f32 v[28:29], v[28:29], v[156:157]
	v_cvt_pk_bf16_f32 v128, v28, v29
	v_pk_mul_f32 v[30:31], v[80:81], v[30:31] op_sel_hi:[0,1]
	v_pk_mul_f32 v[30:31], v[30:31], v[158:159]
	v_cvt_pk_bf16_f32 v129, v30, v31
	v_pk_mul_f32 v[32:33], v[80:81], v[32:33] op_sel_hi:[0,1]
	v_pk_mul_f32 v[32:33], v[32:33], v[180:181]
	v_cvt_pk_bf16_f32 v130, v32, v33
	v_pk_mul_f32 v[34:35], v[80:81], v[34:35] op_sel_hi:[0,1]
	v_pk_mul_f32 v[34:35], v[34:35], v[182:183]
	v_cvt_pk_bf16_f32 v131, v34, v35
	v_pk_mul_f32 v[212:213], v[96:97], v[212:213] op_sel_hi:[0,1]
	v_pk_mul_f32 v[212:213], v[212:213], v[148:149]
	v_cvt_pk_bf16_f32 v132, v212, v213
	v_pk_mul_f32 v[214:215], v[96:97], v[214:215] op_sel_hi:[0,1]
	v_pk_mul_f32 v[214:215], v[214:215], v[150:151]
	v_cvt_pk_bf16_f32 v133, v214, v215
	v_pk_mul_f32 v[216:217], v[96:97], v[216:217] op_sel_hi:[0,1]
	v_pk_mul_f32 v[216:217], v[216:217], v[152:153]
	v_cvt_pk_bf16_f32 v134, v216, v217
	v_pk_mul_f32 v[218:219], v[96:97], v[218:219] op_sel_hi:[0,1]
	v_pk_mul_f32 v[218:219], v[218:219], v[154:155]
	v_cvt_pk_bf16_f32 v135, v218, v219
	v_pk_mul_f32 v[220:221], v[96:97], v[220:221] op_sel_hi:[0,1]
	v_pk_mul_f32 v[220:221], v[220:221], v[156:157]
	v_cvt_pk_bf16_f32 v136, v220, v221
	v_pk_mul_f32 v[222:223], v[96:97], v[222:223] op_sel_hi:[0,1]
	v_pk_mul_f32 v[222:223], v[222:223], v[158:159]
	v_cvt_pk_bf16_f32 v137, v222, v223
	v_pk_mul_f32 v[224:225], v[96:97], v[224:225] op_sel_hi:[0,1]
	v_pk_mul_f32 v[224:225], v[224:225], v[180:181]
	v_cvt_pk_bf16_f32 v138, v224, v225
	v_pk_mul_f32 v[226:227], v[96:97], v[226:227] op_sel_hi:[0,1]
	v_pk_mul_f32 v[226:227], v[226:227], v[182:183]
	v_cvt_pk_bf16_f32 v139, v226, v227
	v_pk_mul_f32 v[228:229], v[98:99], v[228:229] op_sel_hi:[0,1]
	v_pk_mul_f32 v[228:229], v[228:229], v[148:149]
	v_cvt_pk_bf16_f32 v140, v228, v229
	v_pk_mul_f32 v[230:231], v[98:99], v[230:231] op_sel_hi:[0,1]
	v_pk_mul_f32 v[230:231], v[230:231], v[150:151]
	v_cvt_pk_bf16_f32 v141, v230, v231
	v_pk_mul_f32 v[232:233], v[98:99], v[232:233] op_sel_hi:[0,1]
	v_pk_mul_f32 v[232:233], v[232:233], v[152:153]
	v_cvt_pk_bf16_f32 v142, v232, v233
	v_pk_mul_f32 v[234:235], v[98:99], v[234:235] op_sel_hi:[0,1]
	v_pk_mul_f32 v[234:235], v[234:235], v[154:155]
	v_cvt_pk_bf16_f32 v143, v234, v235
	v_pk_mul_f32 v[236:237], v[98:99], v[236:237] op_sel_hi:[0,1]
	v_pk_mul_f32 v[236:237], v[236:237], v[156:157]
	v_cvt_pk_bf16_f32 v144, v236, v237
	v_pk_mul_f32 v[238:239], v[98:99], v[238:239] op_sel_hi:[0,1]
	v_pk_mul_f32 v[238:239], v[238:239], v[158:159]
	v_cvt_pk_bf16_f32 v145, v238, v239
	v_pk_mul_f32 v[240:241], v[98:99], v[240:241] op_sel_hi:[0,1]
	v_pk_mul_f32 v[240:241], v[240:241], v[180:181]
	v_cvt_pk_bf16_f32 v146, v240, v241
	v_pk_mul_f32 v[242:243], v[98:99], v[242:243] op_sel_hi:[0,1]
	v_pk_mul_f32 v[242:243], v[242:243], v[182:183]
	v_cvt_pk_bf16_f32 v147, v242, v243
	ds_read2_b32 v[84:85], v186 offset0:131 offset1:130
	ds_read2_b32 v[86:87], v186 offset0:129 offset1:128
	ds_read2_b32 v[88:89], v186 offset0:115 offset1:114
	ds_read2_b32 v[90:91], v186 offset0:113 offset1:112
	ds_read2_b32 v[92:93], v186 offset0:99 offset1:98
	ds_read2_b32 v[94:95], v186 offset0:97 offset1:96
	ds_read2_b32 v[96:97], v186 offset0:83 offset1:82
	ds_read2_b32 v[98:99], v186 offset0:81 offset1:80
	ds_read2_b32 v[40:41], v186 offset0:67 offset1:66
	ds_read2_b32 v[42:43], v186 offset0:65 offset1:64
	s_waitcnt lgkmcnt(0)
; #define MFMA16(a, b, c) __builtin_amdgcn_mfma_f32_16x16x32_bf16((a), (b), (c), 0, 0, 0)
; template <int PAR> __device__ __forceinline__ void attn_sub(const bf16* KS, const bf16* VT, const float* BTg, const float* gq, float sink2, int n, int ti, int hq, const u32x4 w0, const u32x4 w1, bf16* MIX, ss_t* ssb, int lane) {
;     ...
;         const bf16* kp = KS + (16 * (tb + t) + fr) * KS_STRIDE + 8 * fq;
;         const bf16x8 k0 = *(const bf16x8*)kp, k1 = *(const bf16x8*)(kp + 32);
;         f32x4 acc = (f32x4){0.f, 0.f, 0.f, 0.f};
;         acc = MFMA16(k0, qf[0], acc); acc = MFMA16(k1, qf[1], acc);
;         const bool tv = (n > 0) || (tb + t >= 8);
; #pragma unroll
;         for (int r = 0; r < 4; ++r) { bool valid = tv; if (rel == 0) valid = valid && (e0 + r >= 1); if (rel == 8) valid = valid && (e0 + r <= 0);
;             const float v = valid ? acc[r] + bp[16 * (8 - rel) + (3 - r)] : -1e30f; acc[r] = v; mx = fmaxf(mx, v); }
;         sc[t] = acc;
	ds_read2_b32 v[72:73], v186 offset0:51 offset1:50
	ds_read2_b32 v[74:75], v186 offset0:49 offset1:48
	ds_read2_b32 v[148:149], v186 offset0:35 offset1:34
	ds_read2_b32 v[150:151], v186 offset0:33 offset1:32
	ds_read2_b32 v[152:153], v186 offset0:19 offset1:18
	ds_read2_b32 v[154:155], v186 offset0:17 offset1:16
	ds_read2_b32 v[156:157], v186 offset0:3 offset1:2
	ds_read2_b32 v[158:159], v186 offset0:1 offset1:0
	s_waitcnt lgkmcnt(0)
	v_cndmask_b32_e64 v84, v195, v84, s[40:41]
	v_cndmask_b32_e64 v156, v156, v195, s[40:41]
	v_cndmask_b32_e64 v85, v195, v85, s[42:43]
	v_cndmask_b32_e64 v157, v157, v195, s[42:43]
	v_cndmask_b32_e64 v86, v195, v86, s[44:45]
	v_cndmask_b32_e64 v158, v158, v195, s[44:45]
	v_cndmask_b32_e64 v87, v195, v87, s[46:47]
	v_cndmask_b32_e64 v159, v159, v195, s[46:47]
	ds_read_b128 v[212:215], v185 offset:0
	ds_read_b128 v[216:219], v185 offset:64
	ds_read_b128 v[220:223], v185 offset:2304
	ds_read_b128 v[224:227], v185 offset:2368
	ds_read_b128 v[228:231], v185 offset:4608
	ds_read_b128 v[232:235], v185 offset:4672
	ds_read_b128 v[48:51], v185 offset:6912
	ds_read_b128 v[52:55], v185 offset:6976
	ds_read_b128 v[56:59], v185 offset:9216
	ds_read_b128 v[60:63], v185 offset:9280
	ds_read_b128 v[64:67], v185 offset:11520
	ds_read_b128 v[68:71], v185 offset:11584
	s_waitcnt lgkmcnt(6)
	v_mfma_f32_16x16x32_bf16 v[4:7], v[212:215], v[116:119], v[84:87]
	v_mfma_f32_16x16x32_bf16 v[8:11], v[220:223], v[116:119], v[88:91]
	v_mfma_f32_16x16x32_bf16 v[12:15], v[228:231], v[116:119], v[92:95]
	v_mfma_f32_16x16x32_bf16 v[4:7], v[216:219], v[120:123], v[4:7]
	v_mfma_f32_16x16x32_bf16 v[8:11], v[224:227], v[120:123], v[8:11]
	v_mfma_f32_16x16x32_bf16 v[12:15], v[232:235], v[120:123], v[12:15]
	ds_read_b128 v[212:215], v185 offset:13824
	ds_read_b128 v[216:219], v185 offset:13888
	ds_read_b128 v[220:223], v185 offset:16128
	ds_read_b128 v[224:227], v185 offset:16192
	ds_read_b128 v[228:231], v185 offset:18432
	ds_read_b128 v[232:235], v185 offset:18496
	s_waitcnt lgkmcnt(6)
	v_mfma_f32_16x16x32_bf16 v[16:19], v[48:51], v[116:119], v[96:99]
	v_mfma_f32_16x16x32_bf16 v[20:23], v[56:59], v[116:119], v[40:43]
	v_mfma_f32_16x16x32_bf16 v[24:27], v[64:67], v[116:119], v[72:75]
	v_mfma_f32_16x16x32_bf16 v[16:19], v[52:55], v[120:123], v[16:19]
	v_mfma_f32_16x16x32_bf16 v[20:23], v[60:63], v[120:123], v[20:23]
	v_mfma_f32_16x16x32_bf16 v[24:27], v[68:71], v[120:123], v[24:27]
	s_cmp_lg_u64 s[36:37], 0
	s_cbranch_scc1 .Lat2_nofix_0_0
	s_add_i32 s27, s26, 0
	s_cmp_ge_i32 s27, 8
	s_cbranch_scc1 .Lat2_ok_0_0
	v_mov_b32_e32 v4, v195
	v_mov_b32_e32 v5, v195
	v_mov_b32_e32 v6, v195
	v_mov_b32_e32 v7, v195

; __device__ __forceinline__ unsigned pkbf(float lo, float hi) { typedef float f2_t __attribute__((ext_vector_type(2))); typedef __bf16 b2_t __attribute__((ext_vector_type(2))); f2_t v = {lo, hi}; b2_t b = __builtin_convertvector(v, b2_t); return __builtin_bit_cast(unsigned, b); }
; #define MFMA16(a, b, c) __builtin_amdgcn_mfma_f32_16x16x32_bf16((a), (b), (c), 0, 0, 0)
; template <int PAR> __device__ __forceinline__ void attn_sub(const bf16* KS, const bf16* VT, const float* BTg, const float* gq, float sink2, int n, int ti, int hq, const u32x4 w0, const u32x4 w1, bf16* MIX, ss_t* ssb, int lane) {
;     ...
;     mx = fmaxf(mx, __shfl_xor(mx, 16)); mx = fmaxf(mx, __shfl_xor(mx, 32));
;     float lsum = 0.f;
; #pragma unroll
;     for (int t = 0; t < 10; ++t) { const int rel = t - PAR; if (rel < 0 || rel > 8) continue;
; #pragma unroll
;         for (int r = 0; r < 4; ++r) { const float p = __builtin_amdgcn_exp2f(sc[t][r] - mx); sc[t][r] = p; lsum += p; } }
;     lsum += __shfl_xor(lsum, 16); lsum += __shfl_xor(lsum, 32);
;     lsum += __builtin_amdgcn_exp2f(sink2 - mx);
;     const float rl = 1.0f / lsum;
;     f32x4 o[4];
; #pragma unroll
;     for (int dt = 0; dt < 4; ++dt) o[dt] = (f32x4){0.f, 0.f, 0.f, 0.f};
; #pragma unroll
;     for (int p = 0; p < 5; ++p) {
;         u32x4 pw; pw.x = pkbf(sc[2 * p][0], sc[2 * p][1]); pw.y = pkbf(sc[2 * p][2], sc[2 * p][3]); pw.z = pkbf(sc[2 * p + 1][0], sc[2 * p + 1][1]); pw.w = pkbf(sc[2 * p + 1][2], sc[2 * p + 1][3]);
;         const bf16x8 pb = __builtin_bit_cast(bf16x8, pw);
; #pragma unroll
;         for (int dt = 0; dt < 4; ++dt) {
;             const bf16* vp = VT + (16 * dt + fr) * VT_STRIDE + 16 * (tb + 2 * p) + 4 * fq;
;             const u32x2 lo = *(const u32x2*)vp, hi = *(const u32x2*)(vp + 16);
;             const u32x4 va = (u32x4){lo.x, lo.y, hi.x, hi.y};
;             o[dt] = MFMA16(__builtin_bit_cast(bf16x8, va), pb, o[dt]);
;         }
.Lat2_ok_0_7:
.Lat2_nofix_0_6:
	v_max3_f32 v197, v4, v5, v184
	v_max3_f32 v197, v6, v7, v197
	v_max3_f32 v197, v8, v9, v197
	v_max3_f32 v197, v10, v11, v197
	v_max3_f32 v197, v12, v13, v197
	v_max3_f32 v197, v14, v15, v197
	v_max3_f32 v197, v16, v17, v197
	v_max3_f32 v197, v18, v19, v197
	v_max3_f32 v197, v20, v21, v197
	v_max3_f32 v197, v22, v23, v197
	v_max3_f32 v197, v24, v25, v197
	v_max3_f32 v197, v26, v27, v197
	v_max3_f32 v197, v28, v29, v197
	v_max3_f32 v197, v30, v31, v197
	v_max3_f32 v197, v32, v33, v197
	v_max3_f32 v197, v34, v35, v197
	v_max3_f32 v197, v36, v37, v197
	v_max3_f32 v197, v38, v39, v197
	v_mov_b32_e32 v0, v197
	s_nop 1
	v_permlane16_swap_b32_e32 v197, v0
	v_max_f32_e32 v197, v197, v0
	v_mov_b32_e32 v0, v197
	s_nop 1
	v_permlane32_swap_b32_e32 v197, v0
	v_max_f32_e32 v197, v197, v0
	v_xor_b32_e32 v196, 0x80000000, v197
	v_pk_add_f32 v[4:5], v[4:5], v[196:197] op_sel_hi:[1,0]
	v_pk_add_f32 v[6:7], v[6:7], v[196:197] op_sel_hi:[1,0]
	v_pk_add_f32 v[8:9], v[8:9], v[196:197] op_sel_hi:[1,0]
	v_pk_add_f32 v[10:11], v[10:11], v[196:197] op_sel_hi:[1,0]
	v_pk_add_f32 v[12:13], v[12:13], v[196:197] op_sel_hi:[1,0]
	v_pk_add_f32 v[14:15], v[14:15], v[196:197] op_sel_hi:[1,0]
	v_pk_add_f32 v[16:17], v[16:17], v[196:197] op_sel_hi:[1,0]
	v_pk_add_f32 v[18:19], v[18:19], v[196:197] op_sel_hi:[1,0]
	v_pk_add_f32 v[20:21], v[20:21], v[196:197] op_sel_hi:[1,0]
	v_pk_add_f32 v[22:23], v[22:23], v[196:197] op_sel_hi:[1,0]
	v_pk_add_f32 v[24:25], v[24:25], v[196:197] op_sel_hi:[1,0]
	v_pk_add_f32 v[26:27], v[26:27], v[196:197] op_sel_hi:[1,0]
	v_pk_add_f32 v[28:29], v[28:29], v[196:197] op_sel_hi:[1,0]
	v_pk_add_f32 v[30:31], v[30:31], v[196:197] op_sel_hi:[1,0]
	v_pk_add_f32 v[32:33], v[32:33], v[196:197] op_sel_hi:[1,0]
	v_pk_add_f32 v[34:35], v[34:35], v[196:197] op_sel_hi:[1,0]
	v_pk_add_f32 v[36:37], v[36:37], v[196:197] op_sel_hi:[1,0]
	v_pk_add_f32 v[38:39], v[38:39], v[196:197] op_sel_hi:[1,0]
	v_sub_f32_e32 v0, v184, v197
	v_exp_f32_e32 v4, v4
	v_exp_f32_e32 v5, v5
	v_exp_f32_e32 v6, v6
	v_exp_f32_e32 v7, v7
	v_exp_f32_e32 v8, v8
	v_exp_f32_e32 v9, v9
	v_exp_f32_e32 v10, v10
	v_exp_f32_e32 v11, v11
	v_exp_f32_e32 v12, v12
	v_exp_f32_e32 v13, v13
	v_exp_f32_e32 v14, v14
	v_exp_f32_e32 v15, v15
	v_exp_f32_e32 v16, v16
	v_exp_f32_e32 v17, v17
	v_exp_f32_e32 v18, v18
	v_exp_f32_e32 v19, v19
	v_exp_f32_e32 v20, v20
	v_exp_f32_e32 v21, v21
	v_exp_f32_e32 v22, v22
	v_exp_f32_e32 v23, v23
	v_exp_f32_e32 v24, v24
	v_exp_f32_e32 v25, v25
	v_exp_f32_e32 v26, v26
	v_exp_f32_e32 v27, v27
	v_exp_f32_e32 v28, v28
	v_exp_f32_e32 v29, v29
	v_exp_f32_e32 v30, v30
	v_exp_f32_e32 v31, v31
	v_exp_f32_e32 v32, v32
	v_exp_f32_e32 v33, v33
	v_exp_f32_e32 v34, v34
	v_exp_f32_e32 v35, v35
	v_exp_f32_e32 v36, v36
	v_exp_f32_e32 v37, v37
	v_exp_f32_e32 v38, v38
	v_exp_f32_e32 v39, v39
	v_exp_f32_e32 v0, v0
	v_pk_add_f32 v[78:79], v[4:5], v[6:7]
	v_pk_add_f32 v[78:79], v[78:79], v[8:9]
	v_pk_add_f32 v[78:79], v[78:79], v[10:11]
	v_pk_add_f32 v[78:79], v[78:79], v[12:13]
	v_pk_add_f32 v[78:79], v[78:79], v[14:15]
	v_pk_add_f32 v[78:79], v[78:79], v[16:17]
	v_pk_add_f32 v[78:79], v[78:79], v[18:19]
	v_pk_add_f32 v[78:79], v[78:79], v[20:21]
	v_pk_add_f32 v[78:79], v[78:79], v[22:23]
	v_pk_add_f32 v[78:79], v[78:79], v[24:25]
	v_pk_add_f32 v[78:79], v[78:79], v[26:27]
	v_pk_add_f32 v[78:79], v[78:79], v[28:29]
	v_pk_add_f32 v[78:79], v[78:79], v[30:31]
	v_pk_add_f32 v[78:79], v[78:79], v[32:33]
	v_pk_add_f32 v[78:79], v[78:79], v[34:35]
	v_pk_add_f32 v[78:79], v[78:79], v[36:37]
	v_pk_add_f32 v[78:79], v[78:79], v[38:39]
	v_add_f32_e32 v1, v78, v79
	v_mov_b32_e32 v3, v1
	s_nop 1
	v_permlane16_swap_b32_e32 v1, v3
	v_add_f32_e32 v1, v1, v3
	v_mov_b32_e32 v3, v1
	s_nop 1
	v_permlane32_swap_b32_e32 v1, v3
	v_add_f32_e32 v1, v1, v3
	v_add_f32_e32 v1, v1, v0
	v_rcp_f32_e32 v198, v1
	v_cvt_pk_bf16_f32 v64, v4, v5
	v_cvt_pk_bf16_f32 v65, v6, v7
	v_cvt_pk_bf16_f32 v66, v8, v9
	v_cvt_pk_bf16_f32 v67, v10, v11
	s_waitcnt lgkmcnt(4)
	s_nop 1
	v_mfma_f32_16x16x32_bf16 v[48:51], v[212:215], v[64:67], 0
	v_mfma_f32_16x16x32_bf16 v[52:55], v[216:219], v[64:67], 0
	v_mfma_f32_16x16x32_bf16 v[56:59], v[220:223], v[64:67], 0
	v_mfma_f32_16x16x32_bf16 v[60:63], v[224:227], v[64:67], 0
	ds_read2_b64 v[212:215], v187 offset0:16 offset1:20
	ds_read2_b64 v[216:219], v188 offset0:16 offset1:20
	ds_read2_b64 v[220:223], v189 offset0:16 offset1:20
	ds_read2_b64 v[224:227], v190 offset0:16 offset1:20
	v_cvt_pk_bf16_f32 v68, v12, v13
	v_cvt_pk_bf16_f32 v69, v14, v15
	v_cvt_pk_bf16_f32 v70, v16, v17
	v_cvt_pk_bf16_f32 v71, v18, v19
	s_waitcnt lgkmcnt(4)
	s_nop 1
	v_mfma_f32_16x16x32_bf16 v[48:51], v[228:231], v[68:71], v[48:51]
	v_mfma_f32_16x16x32_bf16 v[52:55], v[232:235], v[68:71], v[52:55]
	v_mfma_f32_16x16x32_bf16 v[56:59], v[236:239], v[68:71], v[56:59]
	v_mfma_f32_16x16x32_bf16 v[60:63], v[240:243], v[68:71], v[60:63]
	ds_read2_b64 v[228:231], v187 offset0:24 offset1:28
	ds_read2_b64 v[232:235], v188 offset0:24 offset1:28
	ds_read2_b64 v[236:239], v189 offset0:24 offset1:28
	ds_read2_b64 v[240:243], v190 offset0:24 offset1:28
	v_cvt_pk_bf16_f32 v64, v20, v21
	v_cvt_pk_bf16_f32 v65, v22, v23
	v_cvt_pk_bf16_f32 v66, v24, v25
	v_cvt_pk_bf16_f32 v67, v26, v27
	s_waitcnt lgkmcnt(4)
; __device__ __forceinline__ void ss_add(ss_t* p, float sq) { const float fl = floorf(sq); const unsigned hi = (unsigned)fl, lo = (unsigned)((sq - fl) * 4294967296.0f); atomicAdd(p, ((ss_t)hi << 32) | (ss_t)lo); }
; __device__ __forceinline__ unsigned pkbf(float lo, float hi) { typedef float f2_t __attribute__((ext_vector_type(2))); typedef __bf16 b2_t __attribute__((ext_vector_type(2))); f2_t v = {lo, hi}; b2_t b = __builtin_convertvector(v, b2_t); return __builtin_bit_cast(unsigned, b); }
; #define MFMA16(a, b, c) __builtin_amdgcn_mfma_f32_16x16x32_bf16((a), (b), (c), 0, 0, 0)
; template <int PAR> __device__ __forceinline__ void attn_sub(const bf16* KS, const bf16* VT, const float* BTg, const float* gq, float sink2, int n, int ti, int hq, const u32x4 w0, const u32x4 w1, bf16* MIX, ss_t* ssb, int lane) {
;     ...
;     for (int p = 0; p < 5; ++p) {
;         u32x4 pw; pw.x = pkbf(sc[2 * p][0], sc[2 * p][1]); pw.y = pkbf(sc[2 * p][2], sc[2 * p][3]); pw.z = pkbf(sc[2 * p + 1][0], sc[2 * p + 1][1]); pw.w = pkbf(sc[2 * p + 1][2], sc[2 * p + 1][3]);
;         const bf16x8 pb = __builtin_bit_cast(bf16x8, pw);
; #pragma unroll
;         for (int dt = 0; dt < 4; ++dt) {
;             const bf16* vp = VT + (16 * dt + fr) * VT_STRIDE + 16 * (tb + 2 * p) + 4 * fq;
;             const u32x2 lo = *(const u32x2*)vp, hi = *(const u32x2*)(vp + 16);
;             const u32x4 va = (u32x4){lo.x, lo.y, hi.x, hi.y};
;             o[dt] = MFMA16(__builtin_bit_cast(bf16x8, va), pb, o[dt]);
;         }
;     }
;     bf16* op = MIX + (size_t)tok * DM + 1024 + hq * 64 + 4 * fq;
;     float sq = 0.f;
; #pragma unroll
;     for (int dt = 0; dt < 4; ++dt) { const f32x4 v = o[dt] * rl; sq += (v[0] * v[0] + v[1] * v[1]) + (v[2] * v[2] + v[3] * v[3]); u32x2 w; w.x = pkbf(v[0], v[1]); w.y = pkbf(v[2], v[3]); *(u32x2*)(op + 16 * dt) = w; }
;     sq += __shfl_xor(sq, 16); sq += __shfl_xor(sq, 32); if (fq == 0) ss_add(ssb + tok, sq);
	s_nop 1
	v_mfma_f32_16x16x32_bf16 v[48:51], v[212:215], v[64:67], v[48:51]
	v_mfma_f32_16x16x32_bf16 v[52:55], v[216:219], v[64:67], v[52:55]
	v_mfma_f32_16x16x32_bf16 v[56:59], v[220:223], v[64:67], v[56:59]
	v_mfma_f32_16x16x32_bf16 v[60:63], v[224:227], v[64:67], v[60:63]
	ds_read_b64 v[212:213], v187 offset:256
	ds_read_b64 v[216:217], v188 offset:256
	ds_read_b64 v[220:221], v189 offset:256
	ds_read_b64 v[224:225], v190 offset:256
	v_cvt_pk_bf16_f32 v68, v28, v29
	v_cvt_pk_bf16_f32 v69, v30, v31
	v_cvt_pk_bf16_f32 v70, v32, v33
	v_cvt_pk_bf16_f32 v71, v34, v35
	s_waitcnt lgkmcnt(4)
	s_nop 1
	v_mfma_f32_16x16x32_bf16 v[48:51], v[228:231], v[68:71], v[48:51]
	v_mfma_f32_16x16x32_bf16 v[52:55], v[232:235], v[68:71], v[52:55]
	v_mfma_f32_16x16x32_bf16 v[56:59], v[236:239], v[68:71], v[56:59]
	v_mfma_f32_16x16x32_bf16 v[60:63], v[240:243], v[68:71], v[60:63]
	v_cvt_pk_bf16_f32 v64, v36, v37
	v_cvt_pk_bf16_f32 v65, v38, v39
	v_mov_b32_e32 v66, 0
	v_mov_b32_e32 v67, 0
	s_waitcnt lgkmcnt(0)
	v_mov_b32_e32 v214, 0
	v_mov_b32_e32 v215, 0
	v_mov_b32_e32 v218, 0
	v_mov_b32_e32 v219, 0
	v_mov_b32_e32 v222, 0
	v_mov_b32_e32 v223, 0
	v_mov_b32_e32 v226, 0
	v_mov_b32_e32 v227, 0
	s_nop 1
	v_mfma_f32_16x16x32_bf16 v[48:51], v[212:215], v[64:67], v[48:51]
	v_mfma_f32_16x16x32_bf16 v[52:55], v[216:219], v[64:67], v[52:55]
	v_mfma_f32_16x16x32_bf16 v[56:59], v[220:223], v[64:67], v[56:59]
	v_mfma_f32_16x16x32_bf16 v[60:63], v[224:227], v[64:67], v[60:63]
	s_nop 7
	s_nop 1
	v_pk_mul_f32 v[48:49], v[198:199], v[48:49] op_sel_hi:[0,1]
	v_pk_mul_f32 v[50:51], v[198:199], v[50:51] op_sel_hi:[0,1]
	v_pk_mul_f32 v[52:53], v[198:199], v[52:53] op_sel_hi:[0,1]
	v_pk_mul_f32 v[54:55], v[198:199], v[54:55] op_sel_hi:[0,1]
	v_pk_mul_f32 v[56:57], v[198:199], v[56:57] op_sel_hi:[0,1]
	v_pk_mul_f32 v[58:59], v[198:199], v[58:59] op_sel_hi:[0,1]
	v_pk_mul_f32 v[60:61], v[198:199], v[60:61] op_sel_hi:[0,1]
	v_pk_mul_f32 v[62:63], v[198:199], v[62:63] op_sel_hi:[0,1]
	v_pk_mul_f32 v[80:81], v[48:49], v[48:49]
	v_pk_fma_f32 v[80:81], v[50:51], v[50:51], v[80:81]
	v_pk_fma_f32 v[80:81], v[52:53], v[52:53], v[80:81]
	v_pk_fma_f32 v[80:81], v[54:55], v[54:55], v[80:81]
	v_pk_fma_f32 v[80:81], v[56:57], v[56:57], v[80:81]
	v_pk_fma_f32 v[80:81], v[58:59], v[58:59], v[80:81]
	v_pk_fma_f32 v[80:81], v[60:61], v[60:61], v[80:81]
	v_pk_fma_f32 v[80:81], v[62:63], v[62:63], v[80:81]
	v_add_f32_e32 v0, v80, v81
	v_cvt_pk_bf16_f32 v48, v48, v49
	v_cvt_pk_bf16_f32 v49, v50, v51
	global_store_dwordx2 v191, v[48:49], s[100:101] offset:0
	v_cvt_pk_bf16_f32 v52, v52, v53
	v_cvt_pk_bf16_f32 v53, v54, v55
	global_store_dwordx2 v191, v[52:53], s[100:101] offset:32
	v_cvt_pk_bf16_f32 v56, v56, v57
	v_cvt_pk_bf16_f32 v57, v58, v59
	global_store_dwordx2 v191, v[56:57], s[100:101] offset:64
	v_cvt_pk_bf16_f32 v60, v60, v61
	v_cvt_pk_bf16_f32 v61, v62, v63
	global_store_dwordx2 v191, v[60:61], s[100:101] offset:96
	v_mov_b32_e32 v1, v0
	s_nop 1
	v_permlane16_swap_b32_e32 v0, v1
	v_add_f32_e32 v0, v0, v1
	v_mov_b32_e32 v1, v0
	s_nop 1
	v_permlane32_swap_b32_e32 v0, v1
	v_add_f32_e32 v0, v0, v1
	s_mov_b64 exec, s[56:57]
	v_floor_f32_e32 v1, v0
	v_sub_f32_e32 v0, v0, v1
	v_mul_f32_e32 v0, 0x4f800000, v0
	v_cvt_u32_f32_e32 v47, v1
	v_cvt_u32_f32_e32 v46, v0
	global_atomic_add_x2 v192, v[46:47], s[100:101] offset:0
	s_mov_b64 exec, -1
	v_add_u32_e32 v191, 0x10000, v191
	ds_read_b128 v[212:215], v185 offset:2304
	ds_read_b128 v[216:219], v185 offset:2368
	ds_read_b128 v[220:223], v185 offset:4608
	ds_read_b128 v[224:227], v185 offset:4672
	ds_read_b128 v[228:231], v185 offset:6912
	ds_read_b128 v[232:235], v185 offset:6976
	ds_read_b128 v[48:51], v185 offset:9216
	ds_read_b128 v[52:55], v185 offset:9280
	ds_read_b128 v[56:59], v185 offset:11520
	ds_read_b128 v[60:63], v185 offset:11584
	ds_read_b128 v[64:67], v185 offset:13824
	ds_read_b128 v[68:71], v185 offset:13888
	s_waitcnt lgkmcnt(6)
	v_mfma_f32_16x16x32_bf16 v[4:7], v[212:215], v[124:127], v[84:87]
	v_mfma_f32_16x16x32_bf16 v[8:11], v[220:223], v[124:127], v[88:91]
	v_mfma_f32_16x16x32_bf16 v[12:15], v[228:231], v[124:127], v[92:95]
	v_mfma_f32_16x16x32_bf16 v[4:7], v[216:219], v[128:131], v[4:7]
	v_mfma_f32_16x16x32_bf16 v[8:11], v[224:227], v[128:131], v[8:11]
	v_mfma_f32_16x16x32_bf16 v[12:15], v[232:235], v[128:131], v[12:15]
	ds_read_b128 v[212:215], v185 offset:16128
	ds_read_b128 v[216:219], v185 offset:16192
	ds_read_b128 v[220:223], v185 offset:18432
	ds_read_b128 v[224:227], v185 offset:18496
	ds_read_b128 v[228:231], v185 offset:20736
	ds_read_b128 v[232:235], v185 offset:20800
	s_waitcnt lgkmcnt(6)
	v_mfma_f32_16x16x32_bf16 v[16:19], v[48:51], v[124:127], v[96:99]
	v_mfma_f32_16x16x32_bf16 v[20:23], v[56:59], v[124:127], v[40:43]
	v_mfma_f32_16x16x32_bf16 v[24:27], v[64:67], v[124:127], v[72:75]
	v_mfma_f32_16x16x32_bf16 v[16:19], v[52:55], v[128:131], v[16:19]
	v_mfma_f32_16x16x32_bf16 v[20:23], v[60:63], v[128:131], v[20:23]
	v_mfma_f32_16x16x32_bf16 v[24:27], v[68:71], v[128:131], v[24:27]
	s_cmp_lg_u64 s[36:37], 0
	s_cbranch_scc1 .Lat2_nofix_1_0
	s_add_i32 s27, s26, 1
	s_cmp_ge_i32 s27, 8
	s_cbranch_scc1 .Lat2_ok_1_0
	v_mov_b32_e32 v4, v195
	v_mov_b32_e32 v5, v195
	v_mov_b32_e32 v6, v195
	v_mov_b32_e32 v7, v195

; __device__ __forceinline__ unsigned pkbf(float lo, float hi) { typedef float f2_t __attribute__((ext_vector_type(2))); typedef __bf16 b2_t __attribute__((ext_vector_type(2))); f2_t v = {lo, hi}; b2_t b = __builtin_convertvector(v, b2_t); return __builtin_bit_cast(unsigned, b); }
; #define MFMA16(a, b, c) __builtin_amdgcn_mfma_f32_16x16x32_bf16((a), (b), (c), 0, 0, 0)
; template <int PAR> __device__ __forceinline__ void attn_sub(const bf16* KS, const bf16* VT, const float* BTg, const float* gq, float sink2, int n, int ti, int hq, const u32x4 w0, const u32x4 w1, bf16* MIX, ss_t* ssb, int lane) {
;     ...
;     mx = fmaxf(mx, __shfl_xor(mx, 16)); mx = fmaxf(mx, __shfl_xor(mx, 32));
;     float lsum = 0.f;
; #pragma unroll
;     for (int t = 0; t < 10; ++t) { const int rel = t - PAR; if (rel < 0 || rel > 8) continue;
; #pragma unroll
;         for (int r = 0; r < 4; ++r) { const float p = __builtin_amdgcn_exp2f(sc[t][r] - mx); sc[t][r] = p; lsum += p; } }
;     lsum += __shfl_xor(lsum, 16); lsum += __shfl_xor(lsum, 32);
;     lsum += __builtin_amdgcn_exp2f(sink2 - mx);
;     const float rl = 1.0f / lsum;
;     f32x4 o[4];
; #pragma unroll
;     for (int dt = 0; dt < 4; ++dt) o[dt] = (f32x4){0.f, 0.f, 0.f, 0.f};
; #pragma unroll
;     for (int p = 0; p < 5; ++p) {
;         u32x4 pw; pw.x = pkbf(sc[2 * p][0], sc[2 * p][1]); pw.y = pkbf(sc[2 * p][2], sc[2 * p][3]); pw.z = pkbf(sc[2 * p + 1][0], sc[2 * p + 1][1]); pw.w = pkbf(sc[2 * p + 1][2], sc[2 * p + 1][3]);
;         const bf16x8 pb = __builtin_bit_cast(bf16x8, pw);
; #pragma unroll
;         for (int dt = 0; dt < 4; ++dt) {
;             const bf16* vp = VT + (16 * dt + fr) * VT_STRIDE + 16 * (tb + 2 * p) + 4 * fq;
;             const u32x2 lo = *(const u32x2*)vp, hi = *(const u32x2*)(vp + 16);
;             const u32x4 va = (u32x4){lo.x, lo.y, hi.x, hi.y};
;             o[dt] = MFMA16(__builtin_bit_cast(bf16x8, va), pb, o[dt]);
;         }
.Lat2_ok_1_6:
.Lat2_nofix_1_6:
	v_max3_f32 v197, v4, v5, v184
	v_max3_f32 v197, v6, v7, v197
	v_max3_f32 v197, v8, v9, v197
	v_max3_f32 v197, v10, v11, v197
	v_max3_f32 v197, v12, v13, v197
	v_max3_f32 v197, v14, v15, v197
	v_max3_f32 v197, v16, v17, v197
	v_max3_f32 v197, v18, v19, v197
	v_max3_f32 v197, v20, v21, v197
	v_max3_f32 v197, v22, v23, v197
	v_max3_f32 v197, v24, v25, v197
	v_max3_f32 v197, v26, v27, v197
	v_max3_f32 v197, v28, v29, v197
	v_max3_f32 v197, v30, v31, v197
	v_max3_f32 v197, v32, v33, v197
	v_max3_f32 v197, v34, v35, v197
	v_max3_f32 v197, v36, v37, v197
	v_max3_f32 v197, v38, v39, v197
	v_mov_b32_e32 v0, v197
	s_nop 1
	v_permlane16_swap_b32_e32 v197, v0
	v_max_f32_e32 v197, v197, v0
	v_mov_b32_e32 v0, v197
	s_nop 1
	v_permlane32_swap_b32_e32 v197, v0
	v_max_f32_e32 v197, v197, v0
	v_xor_b32_e32 v196, 0x80000000, v197
	v_pk_add_f32 v[4:5], v[4:5], v[196:197] op_sel_hi:[1,0]
	v_pk_add_f32 v[6:7], v[6:7], v[196:197] op_sel_hi:[1,0]
	v_pk_add_f32 v[8:9], v[8:9], v[196:197] op_sel_hi:[1,0]
	v_pk_add_f32 v[10:11], v[10:11], v[196:197] op_sel_hi:[1,0]
	v_pk_add_f32 v[12:13], v[12:13], v[196:197] op_sel_hi:[1,0]
	v_pk_add_f32 v[14:15], v[14:15], v[196:197] op_sel_hi:[1,0]
	v_pk_add_f32 v[16:17], v[16:17], v[196:197] op_sel_hi:[1,0]
	v_pk_add_f32 v[18:19], v[18:19], v[196:197] op_sel_hi:[1,0]
	v_pk_add_f32 v[20:21], v[20:21], v[196:197] op_sel_hi:[1,0]
	v_pk_add_f32 v[22:23], v[22:23], v[196:197] op_sel_hi:[1,0]
	v_pk_add_f32 v[24:25], v[24:25], v[196:197] op_sel_hi:[1,0]
	v_pk_add_f32 v[26:27], v[26:27], v[196:197] op_sel_hi:[1,0]
	v_pk_add_f32 v[28:29], v[28:29], v[196:197] op_sel_hi:[1,0]
	v_pk_add_f32 v[30:31], v[30:31], v[196:197] op_sel_hi:[1,0]
	v_pk_add_f32 v[32:33], v[32:33], v[196:197] op_sel_hi:[1,0]
	v_pk_add_f32 v[34:35], v[34:35], v[196:197] op_sel_hi:[1,0]
	v_pk_add_f32 v[36:37], v[36:37], v[196:197] op_sel_hi:[1,0]
	v_pk_add_f32 v[38:39], v[38:39], v[196:197] op_sel_hi:[1,0]
	v_sub_f32_e32 v0, v184, v197
	v_exp_f32_e32 v4, v4
	v_exp_f32_e32 v5, v5
	v_exp_f32_e32 v6, v6
	v_exp_f32_e32 v7, v7
	v_exp_f32_e32 v8, v8
	v_exp_f32_e32 v9, v9
	v_exp_f32_e32 v10, v10
	v_exp_f32_e32 v11, v11
	v_exp_f32_e32 v12, v12
	v_exp_f32_e32 v13, v13
	v_exp_f32_e32 v14, v14
	v_exp_f32_e32 v15, v15
	v_exp_f32_e32 v16, v16
	v_exp_f32_e32 v17, v17
	v_exp_f32_e32 v18, v18
	v_exp_f32_e32 v19, v19
	v_exp_f32_e32 v20, v20
	v_exp_f32_e32 v21, v21
	v_exp_f32_e32 v22, v22
	v_exp_f32_e32 v23, v23
	v_exp_f32_e32 v24, v24
	v_exp_f32_e32 v25, v25
	v_exp_f32_e32 v26, v26
	v_exp_f32_e32 v27, v27
	v_exp_f32_e32 v28, v28
	v_exp_f32_e32 v29, v29
	v_exp_f32_e32 v30, v30
	v_exp_f32_e32 v31, v31
	v_exp_f32_e32 v32, v32
	v_exp_f32_e32 v33, v33
	v_exp_f32_e32 v34, v34
	v_exp_f32_e32 v35, v35
	v_exp_f32_e32 v36, v36
	v_exp_f32_e32 v37, v37
	v_exp_f32_e32 v38, v38
	v_exp_f32_e32 v39, v39
	v_exp_f32_e32 v0, v0
	v_pk_add_f32 v[78:79], v[4:5], v[6:7]
	v_pk_add_f32 v[78:79], v[78:79], v[8:9]
	v_pk_add_f32 v[78:79], v[78:79], v[10:11]
	v_pk_add_f32 v[78:79], v[78:79], v[12:13]
	v_pk_add_f32 v[78:79], v[78:79], v[14:15]
	v_pk_add_f32 v[78:79], v[78:79], v[16:17]
	v_pk_add_f32 v[78:79], v[78:79], v[18:19]
	v_pk_add_f32 v[78:79], v[78:79], v[20:21]
	v_pk_add_f32 v[78:79], v[78:79], v[22:23]
	v_pk_add_f32 v[78:79], v[78:79], v[24:25]
	v_pk_add_f32 v[78:79], v[78:79], v[26:27]
	v_pk_add_f32 v[78:79], v[78:79], v[28:29]
	v_pk_add_f32 v[78:79], v[78:79], v[30:31]
	v_pk_add_f32 v[78:79], v[78:79], v[32:33]
	v_pk_add_f32 v[78:79], v[78:79], v[34:35]
	v_pk_add_f32 v[78:79], v[78:79], v[36:37]
	v_pk_add_f32 v[78:79], v[78:79], v[38:39]
	v_add_f32_e32 v1, v78, v79
	v_mov_b32_e32 v3, v1
	s_nop 1
	v_permlane16_swap_b32_e32 v1, v3
	v_add_f32_e32 v1, v1, v3
	v_mov_b32_e32 v3, v1
	s_nop 1
	v_permlane32_swap_b32_e32 v1, v3
	v_add_f32_e32 v1, v1, v3
	v_add_f32_e32 v1, v1, v0
	v_rcp_f32_e32 v198, v1
	v_cvt_pk_bf16_f32 v64, v4, v5
	v_cvt_pk_bf16_f32 v65, v6, v7
	v_cvt_pk_bf16_f32 v66, v8, v9
	v_cvt_pk_bf16_f32 v67, v10, v11
	s_waitcnt lgkmcnt(4)
	s_nop 1
	v_mfma_f32_16x16x32_bf16 v[48:51], v[212:215], v[64:67], 0
	v_mfma_f32_16x16x32_bf16 v[52:55], v[216:219], v[64:67], 0
	v_mfma_f32_16x16x32_bf16 v[56:59], v[220:223], v[64:67], 0
	v_mfma_f32_16x16x32_bf16 v[60:63], v[224:227], v[64:67], 0
	ds_read2_b64 v[212:215], v187 offset0:20 offset1:24
	ds_read2_b64 v[216:219], v188 offset0:20 offset1:24
	ds_read2_b64 v[220:223], v189 offset0:20 offset1:24
	ds_read2_b64 v[224:227], v190 offset0:20 offset1:24
	v_cvt_pk_bf16_f32 v68, v12, v13
	v_cvt_pk_bf16_f32 v69, v14, v15
	v_cvt_pk_bf16_f32 v70, v16, v17
	v_cvt_pk_bf16_f32 v71, v18, v19
	s_waitcnt lgkmcnt(4)
	s_nop 1
	v_mfma_f32_16x16x32_bf16 v[48:51], v[228:231], v[68:71], v[48:51]
	v_mfma_f32_16x16x32_bf16 v[52:55], v[232:235], v[68:71], v[52:55]
	v_mfma_f32_16x16x32_bf16 v[56:59], v[236:239], v[68:71], v[56:59]
	v_mfma_f32_16x16x32_bf16 v[60:63], v[240:243], v[68:71], v[60:63]
	ds_read2_b64 v[228:231], v187 offset0:28 offset1:32
	ds_read2_b64 v[232:235], v188 offset0:28 offset1:32
	ds_read2_b64 v[236:239], v189 offset0:28 offset1:32
	ds_read2_b64 v[240:243], v190 offset0:28 offset1:32
	v_cvt_pk_bf16_f32 v64, v20, v21
	v_cvt_pk_bf16_f32 v65, v22, v23
	v_cvt_pk_bf16_f32 v66, v24, v25
	v_cvt_pk_bf16_f32 v67, v26, v27
	s_waitcnt lgkmcnt(4)
; __device__ __forceinline__ void ss_add(ss_t* p, float sq) { const float fl = floorf(sq); const unsigned hi = (unsigned)fl, lo = (unsigned)((sq - fl) * 4294967296.0f); atomicAdd(p, ((ss_t)hi << 32) | (ss_t)lo); }
; __device__ __forceinline__ unsigned pkbf(float lo, float hi) { typedef float f2_t __attribute__((ext_vector_type(2))); typedef __bf16 b2_t __attribute__((ext_vector_type(2))); f2_t v = {lo, hi}; b2_t b = __builtin_convertvector(v, b2_t); return __builtin_bit_cast(unsigned, b); }
; #define MFMA16(a, b, c) __builtin_amdgcn_mfma_f32_16x16x32_bf16((a), (b), (c), 0, 0, 0)
; template <int PAR> __device__ __forceinline__ void attn_sub(const bf16* KS, const bf16* VT, const float* BTg, const float* gq, float sink2, int n, int ti, int hq, const u32x4 w0, const u32x4 w1, bf16* MIX, ss_t* ssb, int lane) {
;     ...
;     for (int p = 0; p < 5; ++p) {
;         u32x4 pw; pw.x = pkbf(sc[2 * p][0], sc[2 * p][1]); pw.y = pkbf(sc[2 * p][2], sc[2 * p][3]); pw.z = pkbf(sc[2 * p + 1][0], sc[2 * p + 1][1]); pw.w = pkbf(sc[2 * p + 1][2], sc[2 * p + 1][3]);
;         const bf16x8 pb = __builtin_bit_cast(bf16x8, pw);
; #pragma unroll
;         for (int dt = 0; dt < 4; ++dt) {
;             const bf16* vp = VT + (16 * dt + fr) * VT_STRIDE + 16 * (tb + 2 * p) + 4 * fq;
;             const u32x2 lo = *(const u32x2*)vp, hi = *(const u32x2*)(vp + 16);
;             const u32x4 va = (u32x4){lo.x, lo.y, hi.x, hi.y};
;             o[dt] = MFMA16(__builtin_bit_cast(bf16x8, va), pb, o[dt]);
;         }
;     }
;     bf16* op = MIX + (size_t)tok * DM + 1024 + hq * 64 + 4 * fq;
;     float sq = 0.f;
; #pragma unroll
;     for (int dt = 0; dt < 4; ++dt) { const f32x4 v = o[dt] * rl; sq += (v[0] * v[0] + v[1] * v[1]) + (v[2] * v[2] + v[3] * v[3]); u32x2 w; w.x = pkbf(v[0], v[1]); w.y = pkbf(v[2], v[3]); *(u32x2*)(op + 16 * dt) = w; }
;     sq += __shfl_xor(sq, 16); sq += __shfl_xor(sq, 32); if (fq == 0) ss_add(ssb + tok, sq);
	s_nop 1
	v_mfma_f32_16x16x32_bf16 v[48:51], v[212:215], v[64:67], v[48:51]
	v_mfma_f32_16x16x32_bf16 v[52:55], v[216:219], v[64:67], v[52:55]
	v_mfma_f32_16x16x32_bf16 v[56:59], v[220:223], v[64:67], v[56:59]
	v_mfma_f32_16x16x32_bf16 v[60:63], v[224:227], v[64:67], v[60:63]
	ds_read_b64 v[212:213], v187 offset:288
	ds_read_b64 v[216:217], v188 offset:288
	ds_read_b64 v[220:221], v189 offset:288
	ds_read_b64 v[224:225], v190 offset:288
	v_cvt_pk_bf16_f32 v68, v28, v29
	v_cvt_pk_bf16_f32 v69, v30, v31
	v_cvt_pk_bf16_f32 v70, v32, v33
	v_cvt_pk_bf16_f32 v71, v34, v35
	s_waitcnt lgkmcnt(4)
	s_nop 1
	v_mfma_f32_16x16x32_bf16 v[48:51], v[228:231], v[68:71], v[48:51]
	v_mfma_f32_16x16x32_bf16 v[52:55], v[232:235], v[68:71], v[52:55]
	v_mfma_f32_16x16x32_bf16 v[56:59], v[236:239], v[68:71], v[56:59]
	v_mfma_f32_16x16x32_bf16 v[60:63], v[240:243], v[68:71], v[60:63]
	v_cvt_pk_bf16_f32 v64, v36, v37
	v_cvt_pk_bf16_f32 v65, v38, v39
	v_mov_b32_e32 v66, 0
	v_mov_b32_e32 v67, 0
	s_waitcnt lgkmcnt(0)
	v_mov_b32_e32 v214, 0
	v_mov_b32_e32 v215, 0
	v_mov_b32_e32 v218, 0
	v_mov_b32_e32 v219, 0
	v_mov_b32_e32 v222, 0
	v_mov_b32_e32 v223, 0
	v_mov_b32_e32 v226, 0
	v_mov_b32_e32 v227, 0
	s_nop 1
	v_mfma_f32_16x16x32_bf16 v[48:51], v[212:215], v[64:67], v[48:51]
	v_mfma_f32_16x16x32_bf16 v[52:55], v[216:219], v[64:67], v[52:55]
	v_mfma_f32_16x16x32_bf16 v[56:59], v[220:223], v[64:67], v[56:59]
	v_mfma_f32_16x16x32_bf16 v[60:63], v[224:227], v[64:67], v[60:63]
	s_nop 7
	s_nop 1
	v_pk_mul_f32 v[48:49], v[198:199], v[48:49] op_sel_hi:[0,1]
	v_pk_mul_f32 v[50:51], v[198:199], v[50:51] op_sel_hi:[0,1]
	v_pk_mul_f32 v[52:53], v[198:199], v[52:53] op_sel_hi:[0,1]
	v_pk_mul_f32 v[54:55], v[198:199], v[54:55] op_sel_hi:[0,1]
	v_pk_mul_f32 v[56:57], v[198:199], v[56:57] op_sel_hi:[0,1]
	v_pk_mul_f32 v[58:59], v[198:199], v[58:59] op_sel_hi:[0,1]
	v_pk_mul_f32 v[60:61], v[198:199], v[60:61] op_sel_hi:[0,1]
	v_pk_mul_f32 v[62:63], v[198:199], v[62:63] op_sel_hi:[0,1]
	v_pk_mul_f32 v[80:81], v[48:49], v[48:49]
	v_pk_fma_f32 v[80:81], v[50:51], v[50:51], v[80:81]
	v_pk_fma_f32 v[80:81], v[52:53], v[52:53], v[80:81]
	v_pk_fma_f32 v[80:81], v[54:55], v[54:55], v[80:81]
	v_pk_fma_f32 v[80:81], v[56:57], v[56:57], v[80:81]
	v_pk_fma_f32 v[80:81], v[58:59], v[58:59], v[80:81]
	v_pk_fma_f32 v[80:81], v[60:61], v[60:61], v[80:81]
	v_pk_fma_f32 v[80:81], v[62:63], v[62:63], v[80:81]
	v_add_f32_e32 v0, v80, v81
	v_cvt_pk_bf16_f32 v48, v48, v49
	v_cvt_pk_bf16_f32 v49, v50, v51
	global_store_dwordx2 v191, v[48:49], s[100:101] offset:0
	v_cvt_pk_bf16_f32 v52, v52, v53
	v_cvt_pk_bf16_f32 v53, v54, v55
	global_store_dwordx2 v191, v[52:53], s[100:101] offset:32
	v_cvt_pk_bf16_f32 v56, v56, v57
	v_cvt_pk_bf16_f32 v57, v58, v59
	global_store_dwordx2 v191, v[56:57], s[100:101] offset:64
	v_cvt_pk_bf16_f32 v60, v60, v61
	v_cvt_pk_bf16_f32 v61, v62, v63
	global_store_dwordx2 v191, v[60:61], s[100:101] offset:96
	v_mov_b32_e32 v1, v0
	s_nop 1
	v_permlane16_swap_b32_e32 v0, v1
	v_add_f32_e32 v0, v0, v1
	v_mov_b32_e32 v1, v0
	s_nop 1
	v_permlane32_swap_b32_e32 v0, v1
	v_add_f32_e32 v0, v0, v1
	s_mov_b64 exec, s[56:57]
	v_floor_f32_e32 v1, v0
	v_sub_f32_e32 v0, v0, v1
	v_mul_f32_e32 v0, 0x4f800000, v0
	v_cvt_u32_f32_e32 v47, v1
	v_cvt_u32_f32_e32 v46, v0
	global_atomic_add_x2 v192, v[46:47], s[100:101] offset:128
	s_mov_b64 exec, -1
	v_add_u32_e32 v191, 0x10000, v191
	ds_read_b128 v[212:215], v185 offset:4608
	ds_read_b128 v[216:219], v185 offset:4672
	ds_read_b128 v[220:223], v185 offset:6912
	ds_read_b128 v[224:227], v185 offset:6976
	ds_read_b128 v[228:231], v185 offset:9216
	ds_read_b128 v[232:235], v185 offset:9280
	ds_read_b128 v[48:51], v185 offset:11520
	ds_read_b128 v[52:55], v185 offset:11584
	ds_read_b128 v[56:59], v185 offset:13824
	ds_read_b128 v[60:63], v185 offset:13888
	ds_read_b128 v[64:67], v185 offset:16128
	ds_read_b128 v[68:71], v185 offset:16192
	s_waitcnt lgkmcnt(6)
	v_mfma_f32_16x16x32_bf16 v[4:7], v[212:215], v[132:135], v[84:87]
	v_mfma_f32_16x16x32_bf16 v[8:11], v[220:223], v[132:135], v[88:91]
	v_mfma_f32_16x16x32_bf16 v[12:15], v[228:231], v[132:135], v[92:95]
	v_mfma_f32_16x16x32_bf16 v[4:7], v[216:219], v[136:139], v[4:7]
	v_mfma_f32_16x16x32_bf16 v[8:11], v[224:227], v[136:139], v[8:11]
	v_mfma_f32_16x16x32_bf16 v[12:15], v[232:235], v[136:139], v[12:15]
	ds_read_b128 v[212:215], v185 offset:18432
	ds_read_b128 v[216:219], v185 offset:18496
	ds_read_b128 v[220:223], v185 offset:20736
	ds_read_b128 v[224:227], v185 offset:20800
	ds_read_b128 v[228:231], v185 offset:23040
	ds_read_b128 v[232:235], v185 offset:23104
	s_waitcnt lgkmcnt(6)
	v_mfma_f32_16x16x32_bf16 v[16:19], v[48:51], v[132:135], v[96:99]
	v_mfma_f32_16x16x32_bf16 v[20:23], v[56:59], v[132:135], v[40:43]
	v_mfma_f32_16x16x32_bf16 v[24:27], v[64:67], v[132:135], v[72:75]
	v_mfma_f32_16x16x32_bf16 v[16:19], v[52:55], v[136:139], v[16:19]
	v_mfma_f32_16x16x32_bf16 v[20:23], v[60:63], v[136:139], v[20:23]
	v_mfma_f32_16x16x32_bf16 v[24:27], v[68:71], v[136:139], v[24:27]
	s_cmp_lg_u64 s[36:37], 0
	s_cbranch_scc1 .Lat2_nofix_2_0
	s_add_i32 s27, s26, 2
	s_cmp_ge_i32 s27, 8
	s_cbranch_scc1 .Lat2_ok_2_0
	v_mov_b32_e32 v4, v195
	v_mov_b32_e32 v5, v195
	v_mov_b32_e32 v6, v195
	v_mov_b32_e32 v7, v195

; __device__ __forceinline__ unsigned pkbf(float lo, float hi) { typedef float f2_t __attribute__((ext_vector_type(2))); typedef __bf16 b2_t __attribute__((ext_vector_type(2))); f2_t v = {lo, hi}; b2_t b = __builtin_convertvector(v, b2_t); return __builtin_bit_cast(unsigned, b); }
; #define MFMA16(a, b, c) __builtin_amdgcn_mfma_f32_16x16x32_bf16((a), (b), (c), 0, 0, 0)
; template <int PAR> __device__ __forceinline__ void attn_sub(const bf16* KS, const bf16* VT, const float* BTg, const float* gq, float sink2, int n, int ti, int hq, const u32x4 w0, const u32x4 w1, bf16* MIX, ss_t* ssb, int lane) {
;     ...
;     mx = fmaxf(mx, __shfl_xor(mx, 16)); mx = fmaxf(mx, __shfl_xor(mx, 32));
;     float lsum = 0.f;
; #pragma unroll
;     for (int t = 0; t < 10; ++t) { const int rel = t - PAR; if (rel < 0 || rel > 8) continue;
; #pragma unroll
;         for (int r = 0; r < 4; ++r) { const float p = __builtin_amdgcn_exp2f(sc[t][r] - mx); sc[t][r] = p; lsum += p; } }
;     lsum += __shfl_xor(lsum, 16); lsum += __shfl_xor(lsum, 32);
;     lsum += __builtin_amdgcn_exp2f(sink2 - mx);
;     const float rl = 1.0f / lsum;
;     f32x4 o[4];
; #pragma unroll
;     for (int dt = 0; dt < 4; ++dt) o[dt] = (f32x4){0.f, 0.f, 0.f, 0.f};
; #pragma unroll
;     for (int p = 0; p < 5; ++p) {
;         u32x4 pw; pw.x = pkbf(sc[2 * p][0], sc[2 * p][1]); pw.y = pkbf(sc[2 * p][2], sc[2 * p][3]); pw.z = pkbf(sc[2 * p + 1][0], sc[2 * p + 1][1]); pw.w = pkbf(sc[2 * p + 1][2], sc[2 * p + 1][3]);
;         const bf16x8 pb = __builtin_bit_cast(bf16x8, pw);
; #pragma unroll
;         for (int dt = 0; dt < 4; ++dt) {
;             const bf16* vp = VT + (16 * dt + fr) * VT_STRIDE + 16 * (tb + 2 * p) + 4 * fq;
;             const u32x2 lo = *(const u32x2*)vp, hi = *(const u32x2*)(vp + 16);
;             const u32x4 va = (u32x4){lo.x, lo.y, hi.x, hi.y};
;             o[dt] = MFMA16(__builtin_bit_cast(bf16x8, va), pb, o[dt]);
;         }
.Lat2_ok_2_5:
.Lat2_nofix_2_3:
	v_max3_f32 v197, v4, v5, v184
	v_max3_f32 v197, v6, v7, v197
	v_max3_f32 v197, v8, v9, v197
	v_max3_f32 v197, v10, v11, v197
	v_max3_f32 v197, v12, v13, v197
	v_max3_f32 v197, v14, v15, v197
	v_max3_f32 v197, v16, v17, v197
	v_max3_f32 v197, v18, v19, v197
	v_max3_f32 v197, v20, v21, v197
	v_max3_f32 v197, v22, v23, v197
	v_max3_f32 v197, v24, v25, v197
	v_max3_f32 v197, v26, v27, v197
	v_max3_f32 v197, v28, v29, v197
	v_max3_f32 v197, v30, v31, v197
	v_max3_f32 v197, v32, v33, v197
	v_max3_f32 v197, v34, v35, v197
	v_max3_f32 v197, v36, v37, v197
	v_max3_f32 v197, v38, v39, v197
	v_mov_b32_e32 v0, v197
	s_nop 1
	v_permlane16_swap_b32_e32 v197, v0
	v_max_f32_e32 v197, v197, v0
	v_mov_b32_e32 v0, v197
	s_nop 1
	v_permlane32_swap_b32_e32 v197, v0
	v_max_f32_e32 v197, v197, v0
	v_xor_b32_e32 v196, 0x80000000, v197
	v_pk_add_f32 v[4:5], v[4:5], v[196:197] op_sel_hi:[1,0]
	v_pk_add_f32 v[6:7], v[6:7], v[196:197] op_sel_hi:[1,0]
	v_pk_add_f32 v[8:9], v[8:9], v[196:197] op_sel_hi:[1,0]
	v_pk_add_f32 v[10:11], v[10:11], v[196:197] op_sel_hi:[1,0]
	v_pk_add_f32 v[12:13], v[12:13], v[196:197] op_sel_hi:[1,0]
	v_pk_add_f32 v[14:15], v[14:15], v[196:197] op_sel_hi:[1,0]
	v_pk_add_f32 v[16:17], v[16:17], v[196:197] op_sel_hi:[1,0]
	v_pk_add_f32 v[18:19], v[18:19], v[196:197] op_sel_hi:[1,0]
	v_pk_add_f32 v[20:21], v[20:21], v[196:197] op_sel_hi:[1,0]
	v_pk_add_f32 v[22:23], v[22:23], v[196:197] op_sel_hi:[1,0]
	v_pk_add_f32 v[24:25], v[24:25], v[196:197] op_sel_hi:[1,0]
	v_pk_add_f32 v[26:27], v[26:27], v[196:197] op_sel_hi:[1,0]
	v_pk_add_f32 v[28:29], v[28:29], v[196:197] op_sel_hi:[1,0]
	v_pk_add_f32 v[30:31], v[30:31], v[196:197] op_sel_hi:[1,0]
	v_pk_add_f32 v[32:33], v[32:33], v[196:197] op_sel_hi:[1,0]
	v_pk_add_f32 v[34:35], v[34:35], v[196:197] op_sel_hi:[1,0]
	v_pk_add_f32 v[36:37], v[36:37], v[196:197] op_sel_hi:[1,0]
	v_pk_add_f32 v[38:39], v[38:39], v[196:197] op_sel_hi:[1,0]
	v_sub_f32_e32 v0, v184, v197
	v_exp_f32_e32 v4, v4
	v_exp_f32_e32 v5, v5
	v_exp_f32_e32 v6, v6
	v_exp_f32_e32 v7, v7
	v_exp_f32_e32 v8, v8
	v_exp_f32_e32 v9, v9
	v_exp_f32_e32 v10, v10
	v_exp_f32_e32 v11, v11
	v_exp_f32_e32 v12, v12
	v_exp_f32_e32 v13, v13
	v_exp_f32_e32 v14, v14
	v_exp_f32_e32 v15, v15
	v_exp_f32_e32 v16, v16
	v_exp_f32_e32 v17, v17
	v_exp_f32_e32 v18, v18
	v_exp_f32_e32 v19, v19
	v_exp_f32_e32 v20, v20
	v_exp_f32_e32 v21, v21
	v_exp_f32_e32 v22, v22
	v_exp_f32_e32 v23, v23
	v_exp_f32_e32 v24, v24
	v_exp_f32_e32 v25, v25
	v_exp_f32_e32 v26, v26
	v_exp_f32_e32 v27, v27
	v_exp_f32_e32 v28, v28
	v_exp_f32_e32 v29, v29
	v_exp_f32_e32 v30, v30
	v_exp_f32_e32 v31, v31
	v_exp_f32_e32 v32, v32
	v_exp_f32_e32 v33, v33
	v_exp_f32_e32 v34, v34
	v_exp_f32_e32 v35, v35
	v_exp_f32_e32 v36, v36
	v_exp_f32_e32 v37, v37
	v_exp_f32_e32 v38, v38
	v_exp_f32_e32 v39, v39
	v_exp_f32_e32 v0, v0
	v_pk_add_f32 v[78:79], v[4:5], v[6:7]
	v_pk_add_f32 v[78:79], v[78:79], v[8:9]
	v_pk_add_f32 v[78:79], v[78:79], v[10:11]
	v_pk_add_f32 v[78:79], v[78:79], v[12:13]
	v_pk_add_f32 v[78:79], v[78:79], v[14:15]
	v_pk_add_f32 v[78:79], v[78:79], v[16:17]
	v_pk_add_f32 v[78:79], v[78:79], v[18:19]
	v_pk_add_f32 v[78:79], v[78:79], v[20:21]
	v_pk_add_f32 v[78:79], v[78:79], v[22:23]
	v_pk_add_f32 v[78:79], v[78:79], v[24:25]
	v_pk_add_f32 v[78:79], v[78:79], v[26:27]
	v_pk_add_f32 v[78:79], v[78:79], v[28:29]
	v_pk_add_f32 v[78:79], v[78:79], v[30:31]
	v_pk_add_f32 v[78:79], v[78:79], v[32:33]
	v_pk_add_f32 v[78:79], v[78:79], v[34:35]
	v_pk_add_f32 v[78:79], v[78:79], v[36:37]
	v_pk_add_f32 v[78:79], v[78:79], v[38:39]
	v_add_f32_e32 v1, v78, v79
	v_mov_b32_e32 v3, v1
	s_nop 1
	v_permlane16_swap_b32_e32 v1, v3
	v_add_f32_e32 v1, v1, v3
	v_mov_b32_e32 v3, v1
	s_nop 1
	v_permlane32_swap_b32_e32 v1, v3
	v_add_f32_e32 v1, v1, v3
	v_add_f32_e32 v1, v1, v0
	v_rcp_f32_e32 v198, v1
	v_cvt_pk_bf16_f32 v64, v4, v5
	v_cvt_pk_bf16_f32 v65, v6, v7
	v_cvt_pk_bf16_f32 v66, v8, v9
	v_cvt_pk_bf16_f32 v67, v10, v11
	s_waitcnt lgkmcnt(4)
	s_nop 1
	v_mfma_f32_16x16x32_bf16 v[48:51], v[212:215], v[64:67], 0
	v_mfma_f32_16x16x32_bf16 v[52:55], v[216:219], v[64:67], 0
	v_mfma_f32_16x16x32_bf16 v[56:59], v[220:223], v[64:67], 0
	v_mfma_f32_16x16x32_bf16 v[60:63], v[224:227], v[64:67], 0
	ds_read2_b64 v[212:215], v187 offset0:24 offset1:28
	ds_read2_b64 v[216:219], v188 offset0:24 offset1:28
	ds_read2_b64 v[220:223], v189 offset0:24 offset1:28
	ds_read2_b64 v[224:227], v190 offset0:24 offset1:28
	v_cvt_pk_bf16_f32 v68, v12, v13
	v_cvt_pk_bf16_f32 v69, v14, v15
	v_cvt_pk_bf16_f32 v70, v16, v17
	v_cvt_pk_bf16_f32 v71, v18, v19
	s_waitcnt lgkmcnt(4)
	s_nop 1
	v_mfma_f32_16x16x32_bf16 v[48:51], v[228:231], v[68:71], v[48:51]
	v_mfma_f32_16x16x32_bf16 v[52:55], v[232:235], v[68:71], v[52:55]
	v_mfma_f32_16x16x32_bf16 v[56:59], v[236:239], v[68:71], v[56:59]
	v_mfma_f32_16x16x32_bf16 v[60:63], v[240:243], v[68:71], v[60:63]
	ds_read2_b64 v[228:231], v187 offset0:32 offset1:36
	ds_read2_b64 v[232:235], v188 offset0:32 offset1:36
	ds_read2_b64 v[236:239], v189 offset0:32 offset1:36
	ds_read2_b64 v[240:243], v190 offset0:32 offset1:36
	v_cvt_pk_bf16_f32 v64, v20, v21
	v_cvt_pk_bf16_f32 v65, v22, v23
	v_cvt_pk_bf16_f32 v66, v24, v25
	v_cvt_pk_bf16_f32 v67, v26, v27
	s_waitcnt lgkmcnt(4)
; __device__ __forceinline__ void ss_add(ss_t* p, float sq) { const float fl = floorf(sq); const unsigned hi = (unsigned)fl, lo = (unsigned)((sq - fl) * 4294967296.0f); atomicAdd(p, ((ss_t)hi << 32) | (ss_t)lo); }
; __device__ __forceinline__ unsigned pkbf(float lo, float hi) { typedef float f2_t __attribute__((ext_vector_type(2))); typedef __bf16 b2_t __attribute__((ext_vector_type(2))); f2_t v = {lo, hi}; b2_t b = __builtin_convertvector(v, b2_t); return __builtin_bit_cast(unsigned, b); }
; #define MFMA16(a, b, c) __builtin_amdgcn_mfma_f32_16x16x32_bf16((a), (b), (c), 0, 0, 0)
; template <int PAR> __device__ __forceinline__ void attn_sub(const bf16* KS, const bf16* VT, const float* BTg, const float* gq, float sink2, int n, int ti, int hq, const u32x4 w0, const u32x4 w1, bf16* MIX, ss_t* ssb, int lane) {
;     ...
;     for (int p = 0; p < 5; ++p) {
;         u32x4 pw; pw.x = pkbf(sc[2 * p][0], sc[2 * p][1]); pw.y = pkbf(sc[2 * p][2], sc[2 * p][3]); pw.z = pkbf(sc[2 * p + 1][0], sc[2 * p + 1][1]); pw.w = pkbf(sc[2 * p + 1][2], sc[2 * p + 1][3]);
;         const bf16x8 pb = __builtin_bit_cast(bf16x8, pw);
; #pragma unroll
;         for (int dt = 0; dt < 4; ++dt) {
;             const bf16* vp = VT + (16 * dt + fr) * VT_STRIDE + 16 * (tb + 2 * p) + 4 * fq;
;             const u32x2 lo = *(const u32x2*)vp, hi = *(const u32x2*)(vp + 16);
;             const u32x4 va = (u32x4){lo.x, lo.y, hi.x, hi.y};
;             o[dt] = MFMA16(__builtin_bit_cast(bf16x8, va), pb, o[dt]);
;         }
;     }
;     bf16* op = MIX + (size_t)tok * DM + 1024 + hq * 64 + 4 * fq;
;     float sq = 0.f;
; #pragma unroll
;     for (int dt = 0; dt < 4; ++dt) { const f32x4 v = o[dt] * rl; sq += (v[0] * v[0] + v[1] * v[1]) + (v[2] * v[2] + v[3] * v[3]); u32x2 w; w.x = pkbf(v[0], v[1]); w.y = pkbf(v[2], v[3]); *(u32x2*)(op + 16 * dt) = w; }
;     sq += __shfl_xor(sq, 16); sq += __shfl_xor(sq, 32); if (fq == 0) ss_add(ssb + tok, sq);
	s_nop 1
	v_mfma_f32_16x16x32_bf16 v[48:51], v[212:215], v[64:67], v[48:51]
	v_mfma_f32_16x16x32_bf16 v[52:55], v[216:219], v[64:67], v[52:55]
	v_mfma_f32_16x16x32_bf16 v[56:59], v[220:223], v[64:67], v[56:59]
	v_mfma_f32_16x16x32_bf16 v[60:63], v[224:227], v[64:67], v[60:63]
	ds_read_b64 v[212:213], v187 offset:320
	ds_read_b64 v[216:217], v188 offset:320
	ds_read_b64 v[220:221], v189 offset:320
	ds_read_b64 v[224:225], v190 offset:320
	v_cvt_pk_bf16_f32 v68, v28, v29
	v_cvt_pk_bf16_f32 v69, v30, v31
	v_cvt_pk_bf16_f32 v70, v32, v33
	v_cvt_pk_bf16_f32 v71, v34, v35
	s_waitcnt lgkmcnt(4)
	s_nop 1
	v_mfma_f32_16x16x32_bf16 v[48:51], v[228:231], v[68:71], v[48:51]
	v_mfma_f32_16x16x32_bf16 v[52:55], v[232:235], v[68:71], v[52:55]
	v_mfma_f32_16x16x32_bf16 v[56:59], v[236:239], v[68:71], v[56:59]
	v_mfma_f32_16x16x32_bf16 v[60:63], v[240:243], v[68:71], v[60:63]
	v_cvt_pk_bf16_f32 v64, v36, v37
	v_cvt_pk_bf16_f32 v65, v38, v39
	v_mov_b32_e32 v66, 0
	v_mov_b32_e32 v67, 0
	s_waitcnt lgkmcnt(0)
	v_mov_b32_e32 v214, 0
	v_mov_b32_e32 v215, 0
	v_mov_b32_e32 v218, 0
	v_mov_b32_e32 v219, 0
	v_mov_b32_e32 v222, 0
	v_mov_b32_e32 v223, 0
	v_mov_b32_e32 v226, 0
	v_mov_b32_e32 v227, 0
	s_nop 1
	v_mfma_f32_16x16x32_bf16 v[48:51], v[212:215], v[64:67], v[48:51]
	v_mfma_f32_16x16x32_bf16 v[52:55], v[216:219], v[64:67], v[52:55]
	v_mfma_f32_16x16x32_bf16 v[56:59], v[220:223], v[64:67], v[56:59]
	v_mfma_f32_16x16x32_bf16 v[60:63], v[224:227], v[64:67], v[60:63]
	s_nop 7
	s_nop 1
	v_pk_mul_f32 v[48:49], v[198:199], v[48:49] op_sel_hi:[0,1]
	v_pk_mul_f32 v[50:51], v[198:199], v[50:51] op_sel_hi:[0,1]
	v_pk_mul_f32 v[52:53], v[198:199], v[52:53] op_sel_hi:[0,1]
	v_pk_mul_f32 v[54:55], v[198:199], v[54:55] op_sel_hi:[0,1]
	v_pk_mul_f32 v[56:57], v[198:199], v[56:57] op_sel_hi:[0,1]
	v_pk_mul_f32 v[58:59], v[198:199], v[58:59] op_sel_hi:[0,1]
	v_pk_mul_f32 v[60:61], v[198:199], v[60:61] op_sel_hi:[0,1]
	v_pk_mul_f32 v[62:63], v[198:199], v[62:63] op_sel_hi:[0,1]
	v_pk_mul_f32 v[80:81], v[48:49], v[48:49]
	v_pk_fma_f32 v[80:81], v[50:51], v[50:51], v[80:81]
	v_pk_fma_f32 v[80:81], v[52:53], v[52:53], v[80:81]
	v_pk_fma_f32 v[80:81], v[54:55], v[54:55], v[80:81]
	v_pk_fma_f32 v[80:81], v[56:57], v[56:57], v[80:81]
	v_pk_fma_f32 v[80:81], v[58:59], v[58:59], v[80:81]
	v_pk_fma_f32 v[80:81], v[60:61], v[60:61], v[80:81]
	v_pk_fma_f32 v[80:81], v[62:63], v[62:63], v[80:81]
	v_add_f32_e32 v0, v80, v81
	v_cvt_pk_bf16_f32 v48, v48, v49
	v_cvt_pk_bf16_f32 v49, v50, v51
	global_store_dwordx2 v191, v[48:49], s[100:101] offset:0
	v_cvt_pk_bf16_f32 v52, v52, v53
	v_cvt_pk_bf16_f32 v53, v54, v55
	global_store_dwordx2 v191, v[52:53], s[100:101] offset:32
	v_cvt_pk_bf16_f32 v56, v56, v57
	v_cvt_pk_bf16_f32 v57, v58, v59
	global_store_dwordx2 v191, v[56:57], s[100:101] offset:64
	v_cvt_pk_bf16_f32 v60, v60, v61
	v_cvt_pk_bf16_f32 v61, v62, v63
	global_store_dwordx2 v191, v[60:61], s[100:101] offset:96
	v_mov_b32_e32 v1, v0
	s_nop 1
	v_permlane16_swap_b32_e32 v0, v1
	v_add_f32_e32 v0, v0, v1
	v_mov_b32_e32 v1, v0
	s_nop 1
	v_permlane32_swap_b32_e32 v0, v1
	v_add_f32_e32 v0, v0, v1
	s_mov_b64 exec, s[56:57]
	v_floor_f32_e32 v1, v0
	v_sub_f32_e32 v0, v0, v1
	v_mul_f32_e32 v0, 0x4f800000, v0
	v_cvt_u32_f32_e32 v47, v1
	v_cvt_u32_f32_e32 v46, v0
	global_atomic_add_x2 v192, v[46:47], s[100:101] offset:256
	s_mov_b64 exec, -1
	v_add_u32_e32 v191, 0x10000, v191
	ds_read_b128 v[212:215], v185 offset:6912
	ds_read_b128 v[216:219], v185 offset:6976
	ds_read_b128 v[220:223], v185 offset:9216
	ds_read_b128 v[224:227], v185 offset:9280
	ds_read_b128 v[228:231], v185 offset:11520
	ds_read_b128 v[232:235], v185 offset:11584
	ds_read_b128 v[48:51], v185 offset:13824
	ds_read_b128 v[52:55], v185 offset:13888
	ds_read_b128 v[56:59], v185 offset:16128
	ds_read_b128 v[60:63], v185 offset:16192
	ds_read_b128 v[64:67], v185 offset:18432
	ds_read_b128 v[68:71], v185 offset:18496
	s_waitcnt lgkmcnt(6)
	v_mfma_f32_16x16x32_bf16 v[4:7], v[212:215], v[140:143], v[84:87]
	v_mfma_f32_16x16x32_bf16 v[8:11], v[220:223], v[140:143], v[88:91]
	v_mfma_f32_16x16x32_bf16 v[12:15], v[228:231], v[140:143], v[92:95]
	v_mfma_f32_16x16x32_bf16 v[4:7], v[216:219], v[144:147], v[4:7]
	v_mfma_f32_16x16x32_bf16 v[8:11], v[224:227], v[144:147], v[8:11]
	v_mfma_f32_16x16x32_bf16 v[12:15], v[232:235], v[144:147], v[12:15]
	ds_read_b128 v[212:215], v185 offset:20736
	ds_read_b128 v[216:219], v185 offset:20800
	ds_read_b128 v[220:223], v185 offset:23040
	ds_read_b128 v[224:227], v185 offset:23104
	ds_read_b128 v[228:231], v185 offset:25344
	ds_read_b128 v[232:235], v185 offset:25408
	s_waitcnt lgkmcnt(6)
	v_mfma_f32_16x16x32_bf16 v[16:19], v[48:51], v[140:143], v[96:99]
	v_mfma_f32_16x16x32_bf16 v[20:23], v[56:59], v[140:143], v[40:43]
	v_mfma_f32_16x16x32_bf16 v[24:27], v[64:67], v[140:143], v[72:75]
	v_mfma_f32_16x16x32_bf16 v[16:19], v[52:55], v[144:147], v[16:19]
	v_mfma_f32_16x16x32_bf16 v[20:23], v[60:63], v[144:147], v[20:23]
	v_mfma_f32_16x16x32_bf16 v[24:27], v[68:71], v[144:147], v[24:27]
	s_cmp_lg_u64 s[36:37], 0
	s_cbranch_scc1 .Lat2_nofix_3_0
	s_add_i32 s27, s26, 3
	s_cmp_ge_i32 s27, 8
	s_cbranch_scc1 .Lat2_ok_3_0
	v_mov_b32_e32 v4, v195
	v_mov_b32_e32 v5, v195
	v_mov_b32_e32 v6, v195
	v_mov_b32_e32 v7, v195

; __device__ __forceinline__ unsigned pkbf(float lo, float hi) { typedef float f2_t __attribute__((ext_vector_type(2))); typedef __bf16 b2_t __attribute__((ext_vector_type(2))); f2_t v = {lo, hi}; b2_t b = __builtin_convertvector(v, b2_t); return __builtin_bit_cast(unsigned, b); }
; #define MFMA16(a, b, c) __builtin_amdgcn_mfma_f32_16x16x32_bf16((a), (b), (c), 0, 0, 0)
; template <int PAR> __device__ __forceinline__ void attn_sub(const bf16* KS, const bf16* VT, const float* BTg, const float* gq, float sink2, int n, int ti, int hq, const u32x4 w0, const u32x4 w1, bf16* MIX, ss_t* ssb, int lane) {
;     ...
;     mx = fmaxf(mx, __shfl_xor(mx, 16)); mx = fmaxf(mx, __shfl_xor(mx, 32));
;     float lsum = 0.f;
; #pragma unroll
;     for (int t = 0; t < 10; ++t) { const int rel = t - PAR; if (rel < 0 || rel > 8) continue;
; #pragma unroll
;         for (int r = 0; r < 4; ++r) { const float p = __builtin_amdgcn_exp2f(sc[t][r] - mx); sc[t][r] = p; lsum += p; } }
;     lsum += __shfl_xor(lsum, 16); lsum += __shfl_xor(lsum, 32);
;     lsum += __builtin_amdgcn_exp2f(sink2 - mx);
;     const float rl = 1.0f / lsum;
;     f32x4 o[4];
; #pragma unroll
;     for (int dt = 0; dt < 4; ++dt) o[dt] = (f32x4){0.f, 0.f, 0.f, 0.f};
; #pragma unroll
;     for (int p = 0; p < 5; ++p) {
;         u32x4 pw; pw.x = pkbf(sc[2 * p][0], sc[2 * p][1]); pw.y = pkbf(sc[2 * p][2], sc[2 * p][3]); pw.z = pkbf(sc[2 * p + 1][0], sc[2 * p + 1][1]); pw.w = pkbf(sc[2 * p + 1][2], sc[2 * p + 1][3]);
;         const bf16x8 pb = __builtin_bit_cast(bf16x8, pw);
; #pragma unroll
;         for (int dt = 0; dt < 4; ++dt) {
;             const bf16* vp = VT + (16 * dt + fr) * VT_STRIDE + 16 * (tb + 2 * p) + 4 * fq;
;             const u32x2 lo = *(const u32x2*)vp, hi = *(const u32x2*)(vp + 16);
;             const u32x4 va = (u32x4){lo.x, lo.y, hi.x, hi.y};
;             o[dt] = MFMA16(__builtin_bit_cast(bf16x8, va), pb, o[dt]);
;         }
.Lat2_ok_3_4:
.Lat2_nofix_3_3:
	v_max3_f32 v197, v4, v5, v184
	v_max3_f32 v197, v6, v7, v197
	v_max3_f32 v197, v8, v9, v197
	v_max3_f32 v197, v10, v11, v197
	v_max3_f32 v197, v12, v13, v197
	v_max3_f32 v197, v14, v15, v197
	v_max3_f32 v197, v16, v17, v197
	v_max3_f32 v197, v18, v19, v197
	v_max3_f32 v197, v20, v21, v197
	v_max3_f32 v197, v22, v23, v197
	v_max3_f32 v197, v24, v25, v197
	v_max3_f32 v197, v26, v27, v197
	v_max3_f32 v197, v28, v29, v197
	v_max3_f32 v197, v30, v31, v197
	v_max3_f32 v197, v32, v33, v197
	v_max3_f32 v197, v34, v35, v197
	v_max3_f32 v197, v36, v37, v197
	v_max3_f32 v197, v38, v39, v197
	v_mov_b32_e32 v0, v197
	s_nop 1
	v_permlane16_swap_b32_e32 v197, v0
	v_max_f32_e32 v197, v197, v0
	v_mov_b32_e32 v0, v197
	s_nop 1
	v_permlane32_swap_b32_e32 v197, v0
	v_max_f32_e32 v197, v197, v0
	v_xor_b32_e32 v196, 0x80000000, v197
	v_pk_add_f32 v[4:5], v[4:5], v[196:197] op_sel_hi:[1,0]
	v_pk_add_f32 v[6:7], v[6:7], v[196:197] op_sel_hi:[1,0]
	v_pk_add_f32 v[8:9], v[8:9], v[196:197] op_sel_hi:[1,0]
	v_pk_add_f32 v[10:11], v[10:11], v[196:197] op_sel_hi:[1,0]
	v_pk_add_f32 v[12:13], v[12:13], v[196:197] op_sel_hi:[1,0]
	v_pk_add_f32 v[14:15], v[14:15], v[196:197] op_sel_hi:[1,0]
	v_pk_add_f32 v[16:17], v[16:17], v[196:197] op_sel_hi:[1,0]
	v_pk_add_f32 v[18:19], v[18:19], v[196:197] op_sel_hi:[1,0]
	v_pk_add_f32 v[20:21], v[20:21], v[196:197] op_sel_hi:[1,0]
	v_pk_add_f32 v[22:23], v[22:23], v[196:197] op_sel_hi:[1,0]
	v_pk_add_f32 v[24:25], v[24:25], v[196:197] op_sel_hi:[1,0]
	v_pk_add_f32 v[26:27], v[26:27], v[196:197] op_sel_hi:[1,0]
	v_pk_add_f32 v[28:29], v[28:29], v[196:197] op_sel_hi:[1,0]
	v_pk_add_f32 v[30:31], v[30:31], v[196:197] op_sel_hi:[1,0]
	v_pk_add_f32 v[32:33], v[32:33], v[196:197] op_sel_hi:[1,0]
	v_pk_add_f32 v[34:35], v[34:35], v[196:197] op_sel_hi:[1,0]
	v_pk_add_f32 v[36:37], v[36:37], v[196:197] op_sel_hi:[1,0]
	v_pk_add_f32 v[38:39], v[38:39], v[196:197] op_sel_hi:[1,0]
	v_sub_f32_e32 v0, v184, v197
	v_exp_f32_e32 v4, v4
	v_exp_f32_e32 v5, v5
	v_exp_f32_e32 v6, v6
	v_exp_f32_e32 v7, v7
	v_exp_f32_e32 v8, v8
	v_exp_f32_e32 v9, v9
	v_exp_f32_e32 v10, v10
	v_exp_f32_e32 v11, v11
	v_exp_f32_e32 v12, v12
	v_exp_f32_e32 v13, v13
	v_exp_f32_e32 v14, v14
	v_exp_f32_e32 v15, v15
	v_exp_f32_e32 v16, v16
	v_exp_f32_e32 v17, v17
	v_exp_f32_e32 v18, v18
	v_exp_f32_e32 v19, v19
	v_exp_f32_e32 v20, v20
	v_exp_f32_e32 v21, v21
	v_exp_f32_e32 v22, v22
	v_exp_f32_e32 v23, v23
	v_exp_f32_e32 v24, v24
	v_exp_f32_e32 v25, v25
	v_exp_f32_e32 v26, v26
	v_exp_f32_e32 v27, v27
	v_exp_f32_e32 v28, v28
	v_exp_f32_e32 v29, v29
	v_exp_f32_e32 v30, v30
	v_exp_f32_e32 v31, v31
	v_exp_f32_e32 v32, v32
	v_exp_f32_e32 v33, v33
	v_exp_f32_e32 v34, v34
	v_exp_f32_e32 v35, v35
	v_exp_f32_e32 v36, v36
	v_exp_f32_e32 v37, v37
	v_exp_f32_e32 v38, v38
	v_exp_f32_e32 v39, v39
	v_exp_f32_e32 v0, v0
	v_pk_add_f32 v[78:79], v[4:5], v[6:7]
	v_pk_add_f32 v[78:79], v[78:79], v[8:9]
	v_pk_add_f32 v[78:79], v[78:79], v[10:11]
	v_pk_add_f32 v[78:79], v[78:79], v[12:13]
	v_pk_add_f32 v[78:79], v[78:79], v[14:15]
	v_pk_add_f32 v[78:79], v[78:79], v[16:17]
	v_pk_add_f32 v[78:79], v[78:79], v[18:19]
	v_pk_add_f32 v[78:79], v[78:79], v[20:21]
	v_pk_add_f32 v[78:79], v[78:79], v[22:23]
	v_pk_add_f32 v[78:79], v[78:79], v[24:25]
	v_pk_add_f32 v[78:79], v[78:79], v[26:27]
	v_pk_add_f32 v[78:79], v[78:79], v[28:29]
	v_pk_add_f32 v[78:79], v[78:79], v[30:31]
	v_pk_add_f32 v[78:79], v[78:79], v[32:33]
	v_pk_add_f32 v[78:79], v[78:79], v[34:35]
	v_pk_add_f32 v[78:79], v[78:79], v[36:37]
	v_pk_add_f32 v[78:79], v[78:79], v[38:39]
	v_add_f32_e32 v1, v78, v79
	v_mov_b32_e32 v3, v1
	s_nop 1
	v_permlane16_swap_b32_e32 v1, v3
	v_add_f32_e32 v1, v1, v3
	v_mov_b32_e32 v3, v1
	s_nop 1
	v_permlane32_swap_b32_e32 v1, v3
	v_add_f32_e32 v1, v1, v3
	v_add_f32_e32 v1, v1, v0
	v_rcp_f32_e32 v198, v1
	v_cvt_pk_bf16_f32 v64, v4, v5
	v_cvt_pk_bf16_f32 v65, v6, v7
	v_cvt_pk_bf16_f32 v66, v8, v9
	v_cvt_pk_bf16_f32 v67, v10, v11
	s_waitcnt lgkmcnt(4)
	s_nop 1
	v_mfma_f32_16x16x32_bf16 v[48:51], v[212:215], v[64:67], 0
	v_mfma_f32_16x16x32_bf16 v[52:55], v[216:219], v[64:67], 0
	v_mfma_f32_16x16x32_bf16 v[56:59], v[220:223], v[64:67], 0
	v_mfma_f32_16x16x32_bf16 v[60:63], v[224:227], v[64:67], 0
	ds_read2_b64 v[212:215], v187 offset0:28 offset1:32
	ds_read2_b64 v[216:219], v188 offset0:28 offset1:32
	ds_read2_b64 v[220:223], v189 offset0:28 offset1:32
	ds_read2_b64 v[224:227], v190 offset0:28 offset1:32
	v_cvt_pk_bf16_f32 v68, v12, v13
	v_cvt_pk_bf16_f32 v69, v14, v15
	v_cvt_pk_bf16_f32 v70, v16, v17
	v_cvt_pk_bf16_f32 v71, v18, v19
	s_waitcnt lgkmcnt(4)
; __device__ __forceinline__ void ss_add(ss_t* p, float sq) { const float fl = floorf(sq); const unsigned hi = (unsigned)fl, lo = (unsigned)((sq - fl) * 4294967296.0f); atomicAdd(p, ((ss_t)hi << 32) | (ss_t)lo); }
; __device__ __forceinline__ unsigned pkbf(float lo, float hi) { typedef float f2_t __attribute__((ext_vector_type(2))); typedef __bf16 b2_t __attribute__((ext_vector_type(2))); f2_t v = {lo, hi}; b2_t b = __builtin_convertvector(v, b2_t); return __builtin_bit_cast(unsigned, b); }
; #define MFMA16(a, b, c) __builtin_amdgcn_mfma_f32_16x16x32_bf16((a), (b), (c), 0, 0, 0)
; template <int PAR> __device__ __forceinline__ void attn_sub(const bf16* KS, const bf16* VT, const float* BTg, const float* gq, float sink2, int n, int ti, int hq, const u32x4 w0, const u32x4 w1, bf16* MIX, ss_t* ssb, int lane) {
;     ...
;     for (int p = 0; p < 5; ++p) {
;         u32x4 pw; pw.x = pkbf(sc[2 * p][0], sc[2 * p][1]); pw.y = pkbf(sc[2 * p][2], sc[2 * p][3]); pw.z = pkbf(sc[2 * p + 1][0], sc[2 * p + 1][1]); pw.w = pkbf(sc[2 * p + 1][2], sc[2 * p + 1][3]);
;         const bf16x8 pb = __builtin_bit_cast(bf16x8, pw);
; #pragma unroll
;         for (int dt = 0; dt < 4; ++dt) {
;             const bf16* vp = VT + (16 * dt + fr) * VT_STRIDE + 16 * (tb + 2 * p) + 4 * fq;
;             const u32x2 lo = *(const u32x2*)vp, hi = *(const u32x2*)(vp + 16);
;             const u32x4 va = (u32x4){lo.x, lo.y, hi.x, hi.y};
;             o[dt] = MFMA16(__builtin_bit_cast(bf16x8, va), pb, o[dt]);
;         }
;     }
;     bf16* op = MIX + (size_t)tok * DM + 1024 + hq * 64 + 4 * fq;
;     float sq = 0.f;
; #pragma unroll
;     for (int dt = 0; dt < 4; ++dt) { const f32x4 v = o[dt] * rl; sq += (v[0] * v[0] + v[1] * v[1]) + (v[2] * v[2] + v[3] * v[3]); u32x2 w; w.x = pkbf(v[0], v[1]); w.y = pkbf(v[2], v[3]); *(u32x2*)(op + 16 * dt) = w; }
;     sq += __shfl_xor(sq, 16); sq += __shfl_xor(sq, 32); if (fq == 0) ss_add(ssb + tok, sq);
	s_nop 1
	v_mfma_f32_16x16x32_bf16 v[48:51], v[228:231], v[68:71], v[48:51]
	v_mfma_f32_16x16x32_bf16 v[52:55], v[232:235], v[68:71], v[52:55]
	v_mfma_f32_16x16x32_bf16 v[56:59], v[236:239], v[68:71], v[56:59]
	v_mfma_f32_16x16x32_bf16 v[60:63], v[240:243], v[68:71], v[60:63]
	ds_read2_b64 v[228:231], v187 offset0:36 offset1:40
	ds_read2_b64 v[232:235], v188 offset0:36 offset1:40
	ds_read2_b64 v[236:239], v189 offset0:36 offset1:40
	ds_read2_b64 v[240:243], v190 offset0:36 offset1:40
	v_cvt_pk_bf16_f32 v64, v20, v21
	v_cvt_pk_bf16_f32 v65, v22, v23
	v_cvt_pk_bf16_f32 v66, v24, v25
	v_cvt_pk_bf16_f32 v67, v26, v27
	s_waitcnt lgkmcnt(4)
	s_nop 1
	v_mfma_f32_16x16x32_bf16 v[48:51], v[212:215], v[64:67], v[48:51]
	v_mfma_f32_16x16x32_bf16 v[52:55], v[216:219], v[64:67], v[52:55]
	v_mfma_f32_16x16x32_bf16 v[56:59], v[220:223], v[64:67], v[56:59]
	v_mfma_f32_16x16x32_bf16 v[60:63], v[224:227], v[64:67], v[60:63]
	ds_read_b64 v[212:213], v187 offset:352
	ds_read_b64 v[216:217], v188 offset:352
	ds_read_b64 v[220:221], v189 offset:352
	ds_read_b64 v[224:225], v190 offset:352
	v_cvt_pk_bf16_f32 v68, v28, v29
	v_cvt_pk_bf16_f32 v69, v30, v31
	v_cvt_pk_bf16_f32 v70, v32, v33
	v_cvt_pk_bf16_f32 v71, v34, v35
	s_waitcnt lgkmcnt(4)
	s_nop 1
	v_mfma_f32_16x16x32_bf16 v[48:51], v[228:231], v[68:71], v[48:51]
	v_mfma_f32_16x16x32_bf16 v[52:55], v[232:235], v[68:71], v[52:55]
	v_mfma_f32_16x16x32_bf16 v[56:59], v[236:239], v[68:71], v[56:59]
	v_mfma_f32_16x16x32_bf16 v[60:63], v[240:243], v[68:71], v[60:63]
	v_cvt_pk_bf16_f32 v64, v36, v37
	v_cvt_pk_bf16_f32 v65, v38, v39
	v_mov_b32_e32 v66, 0
	v_mov_b32_e32 v67, 0
	s_waitcnt lgkmcnt(0)
	v_mov_b32_e32 v214, 0
	v_mov_b32_e32 v215, 0
	v_mov_b32_e32 v218, 0
	v_mov_b32_e32 v219, 0
	v_mov_b32_e32 v222, 0
	v_mov_b32_e32 v223, 0
	v_mov_b32_e32 v226, 0
	v_mov_b32_e32 v227, 0
	s_nop 1
	v_mfma_f32_16x16x32_bf16 v[48:51], v[212:215], v[64:67], v[48:51]
	v_mfma_f32_16x16x32_bf16 v[52:55], v[216:219], v[64:67], v[52:55]
	v_mfma_f32_16x16x32_bf16 v[56:59], v[220:223], v[64:67], v[56:59]
	v_mfma_f32_16x16x32_bf16 v[60:63], v[224:227], v[64:67], v[60:63]
	s_nop 7
	s_nop 1
	v_pk_mul_f32 v[48:49], v[198:199], v[48:49] op_sel_hi:[0,1]
	v_pk_mul_f32 v[50:51], v[198:199], v[50:51] op_sel_hi:[0,1]
	v_pk_mul_f32 v[52:53], v[198:199], v[52:53] op_sel_hi:[0,1]
	v_pk_mul_f32 v[54:55], v[198:199], v[54:55] op_sel_hi:[0,1]
	v_pk_mul_f32 v[56:57], v[198:199], v[56:57] op_sel_hi:[0,1]
	v_pk_mul_f32 v[58:59], v[198:199], v[58:59] op_sel_hi:[0,1]
	v_pk_mul_f32 v[60:61], v[198:199], v[60:61] op_sel_hi:[0,1]
	v_pk_mul_f32 v[62:63], v[198:199], v[62:63] op_sel_hi:[0,1]
	v_pk_mul_f32 v[80:81], v[48:49], v[48:49]
	v_pk_fma_f32 v[80:81], v[50:51], v[50:51], v[80:81]
	v_pk_fma_f32 v[80:81], v[52:53], v[52:53], v[80:81]
	v_pk_fma_f32 v[80:81], v[54:55], v[54:55], v[80:81]
	v_pk_fma_f32 v[80:81], v[56:57], v[56:57], v[80:81]
	v_pk_fma_f32 v[80:81], v[58:59], v[58:59], v[80:81]
	v_pk_fma_f32 v[80:81], v[60:61], v[60:61], v[80:81]
	v_pk_fma_f32 v[80:81], v[62:63], v[62:63], v[80:81]
	v_add_f32_e32 v0, v80, v81
	v_cvt_pk_bf16_f32 v48, v48, v49
	v_cvt_pk_bf16_f32 v49, v50, v51
	global_store_dwordx2 v191, v[48:49], s[100:101] offset:0
	v_cvt_pk_bf16_f32 v52, v52, v53
	v_cvt_pk_bf16_f32 v53, v54, v55
	global_store_dwordx2 v191, v[52:53], s[100:101] offset:32
	v_cvt_pk_bf16_f32 v56, v56, v57
	v_cvt_pk_bf16_f32 v57, v58, v59
	global_store_dwordx2 v191, v[56:57], s[100:101] offset:64
	v_cvt_pk_bf16_f32 v60, v60, v61
	v_cvt_pk_bf16_f32 v61, v62, v63
	global_store_dwordx2 v191, v[60:61], s[100:101] offset:96
	v_mov_b32_e32 v1, v0
	s_nop 1
	v_permlane16_swap_b32_e32 v0, v1
	v_add_f32_e32 v0, v0, v1
	v_mov_b32_e32 v1, v0
	s_nop 1
	v_permlane32_swap_b32_e32 v0, v1
	v_add_f32_e32 v0, v0, v1
	s_mov_b64 exec, s[56:57]
	v_floor_f32_e32 v1, v0
	v_sub_f32_e32 v0, v0, v1
	v_mul_f32_e32 v0, 0x4f800000, v0
	v_cvt_u32_f32_e32 v47, v1
	v_cvt_u32_f32_e32 v46, v0
	global_atomic_add_x2 v192, v[46:47], s[100:101] offset:384
	s_mov_b64 exec, -1
